# hot loop heads (8-phase GEMM, merge/w_out K-loops incl. staggered copies, toeplitz) pinned to 64-byte boundaries
# speedup vs baseline: 1.0023x; 1.0023x over previous
; DI void wait_vm0() { asm volatile("s_waitcnt vmcnt(0)" ::: "memory"); }
; DI int otid() { int t = threadIdx.x; asm volatile("" : "+v"(t)); return t; }
; template <int MB, bool SWAP>
; DI void gemm_kloop(f32x16 (&acc)[MB][2], const h16* __restrict__ A, int lda, const h16* __restrict__ B, int ldb, int K, char* lds) {
;     ...
;   const int tid = otid(), w = tid >> 6, lane = tid & 63;
;   const int wr = w >> 2, wc = w & 3;
;   const int lrow = w * 8 + (lane >> 3), pch = lane & 7;
;   const int gch = pch ^ ((lrow >> 1) & 7);
;   const unsigned voa = (unsigned)(lrow * lda + gch * 8) * 2u, vob = (unsigned)(lrow * ldb + gch * 8) * 2u;
;   const int lofs = lrow * 128 + pch * 16;
;   const int r32 = lane & 31, hh = lane >> 5, sw = (r32 >> 1) & 7;
;   const int a_rd = (wr * 32 * MB + r32) * 128;
;   const int b_rd = A_BYTES + (wc * 64 + r32) * 128;
;   const int nk = K >> 6;
;   constexpr int NP = MB + 4;
;   auto piece = [&](int p, int kt, int buf) {
;     char* s = lds + buf * STAGE;
;     if (p < MB) __builtin_amdgcn_global_load_lds((const unsigned*)((const char*)(A + (size_t)p * 64 * lda + kt * 64) + voa), (unsigned*)(s + p * 8192 + lofs), 16, 0, 0);
;     else __builtin_amdgcn_global_load_lds((const unsigned*)((const char*)(B + (size_t)(p - MB) * 64 * ldb + kt * 64) + vob), (unsigned*)(s + A_BYTES + (p - MB) * 8192 + lofs), 16, 0, 0);
;   };
;   wait_vm0();
; #pragma unroll
;   for (int p = 0; p < NP; ++p) piece(p, 0, 0);
; #pragma unroll
;   for (int p = 0; p < NP; ++p) piece(p, 1, 1);
; template <int MB>
; DI void merge_tile(const Params& P, int layer, size_t row0, int nt, char* smem) {
;     ...
;     zero_acc<MB>(pa2);
;     gemm_kloop<MB, true>(pa2, hb + row0 * LDH, LDH, winT + (size_t)(G_OFF + n * 1024 + nt * 256) * LDH, LDH, D, smem);
.LBB0_39:
	v_mov_b32_e32 v5, v208
	s_lshl_b32 vcc_lo, s45, 10
	v_ashrrev_i32_e32 v11, 3, v5
	v_bfe_u32 v12, v5, 3, 3
	v_and_or_b32 v0, v11, -8, v12
	v_lshrrev_b32_e32 v1, 1, v0
	v_xor_b32_e32 v1, v1, v5
	v_lshlrev_b32_e32 v1, 3, v1
	v_mul_lo_u32 v2, v0, s6
	v_and_b32_e32 v13, 56, v1
	v_or_b32_e32 v1, v13, v2
	v_lshlrev_b32_e32 v128, 1, v1
	v_lshlrev_b32_e32 v1, 4, v5
	v_and_b32_e32 v1, 0x70, v1
	v_lshl_or_b32 v8, v0, 7, v1
	v_add_u32_e32 v10, 0, v8
	v_add_u32_e32 v15, 0x2000, v10
	v_readfirstlane_b32 s33, v10
	s_add_i32 s24, s74, vcc_lo
	s_nop 0
	v_lshl_add_u64 v[2:3], s[50:51], 0, v[128:129]
	s_mov_b32 m0, s33
	s_mov_b64 s[52:53], 0x22000
	v_readfirstlane_b32 s33, v15
	s_mul_i32 s84, s24, 0x440
	global_load_lds_dwordx4 v128, s[50:51]
	v_lshl_add_u64 v[6:7], v[2:3], 0, s[52:53]
	s_mov_b32 m0, s33
	s_lshl_b64 s[24:25], s[84:85], 1
	global_load_lds_dwordx4 v[6:7], off
	v_add_u32_e32 v6, 0x4000, v10
	s_add_u32 s24, s96, s24
	v_and_b32_e32 v0, 31, v5
	v_lshrrev_b32_e32 v1, 2, v5
	v_readfirstlane_b32 s33, v6
	s_addc_u32 s25, s97, s25
	v_and_or_b32 v14, v1, s7, v0
	v_lshlrev_b32_e32 v0, 7, v5
	s_mov_b32 m0, s33
	v_add_u32_e32 v15, 0x6000, v10
	v_and_b32_e32 v4, 0x6f80, v0
	v_lshl_add_u64 v[0:1], s[24:25], 0, v[128:129]
	global_load_lds_dwordx4 v128, s[24:25]
	v_readfirstlane_b32 s24, v15
	v_lshl_add_u64 v[6:7], v[0:1], 0, s[52:53]
	s_mov_b32 m0, s24
	s_mov_b64 s[24:25], 0x44000
	v_add_u32_e32 v15, 0x8000, v10
	global_load_lds_dwordx4 v[6:7], off
	v_lshl_add_u64 v[6:7], v[0:1], 0, s[24:25]
	v_readfirstlane_b32 s24, v15
	s_mov_b32 m0, s24
	s_mov_b64 s[24:25], 0x66000
	v_add_u32_e32 v15, 0xa000, v10
	global_load_lds_dwordx4 v[6:7], off
	v_lshl_add_u64 v[6:7], v[0:1], 0, s[24:25]
	v_readfirstlane_b32 s24, v15
	s_mov_b32 m0, s24
	v_lshl_add_u64 v[2:3], v[2:3], 0, s[22:23]
	global_load_lds_dwordx4 v[6:7], off
	v_add_u32_e32 v7, 0xc000, v10
	v_lshrrev_b32_e32 v9, 1, v5
	v_readfirstlane_b32 s24, v7
	s_mov_b32 m0, s24
	v_add_u32_e32 v7, s8, v8
	global_load_lds_dwordx4 v[2:3], off
	v_add_u32_e32 v2, 0xe000, v10
	v_bfe_u32 v15, v5, 5, 1
	v_readfirstlane_b32 s24, v2
	s_mov_b32 m0, s24
	v_readfirstlane_b32 s24, v7
	global_load_lds_dwordx4 v128, s[86:87]
	v_lshl_add_u64 v[2:3], v[0:1], 0, s[22:23]
	s_mov_b32 m0, s24
	s_mov_b64 s[24:25], 0x22080
	v_add_u32_e32 v7, s9, v8
	global_load_lds_dwordx4 v[2:3], off
	v_lshl_add_u64 v[2:3], v[0:1], 0, s[24:25]
	v_readfirstlane_b32 s24, v7
	s_mov_b32 m0, s24
	s_mov_b64 s[24:25], 0x44080
	v_add_u32_e32 v7, s79, v8
	global_load_lds_dwordx4 v[2:3], off
	v_lshl_add_u64 v[2:3], v[0:1], 0, s[24:25]
	v_readfirstlane_b32 s24, v7
	s_mov_b32 m0, s24
	s_mov_b64 s[24:25], 0x66080
	global_load_lds_dwordx4 v[2:3], off
	v_add_u32_e32 v2, s10, v8
	v_lshl_add_u64 v[0:1], v[0:1], 0, s[24:25]
	v_readfirstlane_b32 s24, v2
	s_mov_b32 m0, s24
	v_lshlrev_b32_e32 v6, 7, v14
	global_load_lds_dwordx4 v[0:1], off
	v_bfe_u32 v0, v5, 1, 3
	v_bitop3_b32 v1, v15, v9, 7 bitop3:0x78
	v_lshlrev_b32_e32 v9, 4, v1
	v_bitop3_b32 v1, v15, v0, 2 bitop3:0x36
	v_lshlrev_b32_e32 v8, 4, v1
	v_bitop3_b32 v1, v15, v0, 4 bitop3:0x36
	v_bitop3_b32 v0, v15, v0, 6 bitop3:0x36
	v_lshlrev_b32_e32 v5, 4, v0
	v_lshrrev_b32_e32 v0, 3, v11
	v_mul_lo_u32 v0, v0, s11
	v_mad_u32_u24 v0, v12, s6, v0
	v_or_b32_e32 v0, v0, v13
	v_lshlrev_b32_e32 v128, 1, v0
	v_lshlrev_b32_e32 v7, 4, v1
	v_lshl_add_u64 v[0:1], s[38:39], 0, v[128:129]
	v_lshl_add_u64 v[2:3], s[42:43], 0, v[128:129]
	s_mov_b64 s[80:81], 0
	s_mov_b32 s24, 0
	v_mov_b32_e32 v64, 0
	v_mov_b32_e32 v65, v197
	v_mov_b32_e32 v66, v197
	v_mov_b32_e32 v67, v197
	v_mov_b32_e32 v68, v197
	v_mov_b32_e32 v69, v197
	v_mov_b32_e32 v70, v197
	v_mov_b32_e32 v71, v197
	v_mov_b32_e32 v72, v197
	v_mov_b32_e32 v73, v197
	v_mov_b32_e32 v74, v197
	v_mov_b32_e32 v75, v197
	v_mov_b32_e32 v76, v197
	v_mov_b32_e32 v77, v197
	v_mov_b32_e32 v78, v197
	v_mov_b32_e32 v79, v197
	v_mov_b32_e32 v80, 0
	v_mov_b32_e32 v81, v197
	v_mov_b32_e32 v82, v197
	v_mov_b32_e32 v83, v197
	v_mov_b32_e32 v84, v197
	v_mov_b32_e32 v85, v197
	v_mov_b32_e32 v86, v197
	v_mov_b32_e32 v87, v197
	v_mov_b32_e32 v88, v197
	v_mov_b32_e32 v89, v197
	v_mov_b32_e32 v90, v197
	v_mov_b32_e32 v91, v197
	v_mov_b32_e32 v92, v197
	v_mov_b32_e32 v93, v197
	v_mov_b32_e32 v94, v197
	v_mov_b32_e32 v95, v197
	v_mov_b32_e32 v96, 0
	v_mov_b32_e32 v97, v197
	v_mov_b32_e32 v98, v197
	v_mov_b32_e32 v99, v197
	v_mov_b32_e32 v100, v197
	v_mov_b32_e32 v101, v197
	v_mov_b32_e32 v102, v197
	v_mov_b32_e32 v103, v197
	v_mov_b32_e32 v104, v197
	v_mov_b32_e32 v105, v197
	v_mov_b32_e32 v106, v197
	v_mov_b32_e32 v107, v197
	v_mov_b32_e32 v108, v197
	v_mov_b32_e32 v109, v197
	v_mov_b32_e32 v110, v197
	v_mov_b32_e32 v111, v197
	v_mov_b32_e32 v112, 0
	v_mov_b32_e32 v113, v197
	v_mov_b32_e32 v114, v197
	v_mov_b32_e32 v115, v197
	v_mov_b32_e32 v116, v197
	v_mov_b32_e32 v117, v197
	v_mov_b32_e32 v118, v197
	v_mov_b32_e32 v119, v197
	v_mov_b32_e32 v120, v197
	v_mov_b32_e32 v121, v197
	v_mov_b32_e32 v122, v197
	v_mov_b32_e32 v123, v197
	v_mov_b32_e32 v124, v197
	v_mov_b32_e32 v125, v197
	v_mov_b32_e32 v126, v197
	v_mov_b32_e32 v127, v197
	s_mov_b64 s[52:53], 0x3308100
	v_readfirstlane_b32 s25, v208
	s_nop 0
	s_lshr_b32 s25, s25, 8
	s_cmp_lg_u32 s25, 0
	s_cbranch_scc1 .Lstg40_top
	.p2align	6
; DI void wait_vm0() { asm volatile("s_waitcnt vmcnt(0)" ::: "memory"); }
; template <int MB, bool SWAP>
; DI void gemm_kloop(f32x16 (&acc)[MB][2], const h16* __restrict__ A, int lda, const h16* __restrict__ B, int ldb, int K, char* lds) {
;     ...
;   for (int kt = 0; kt < nk; ++kt) {
;     if (kt + 1 < nk) { if (MB == 2) asm volatile("s_waitcnt vmcnt(6)" ::: "memory"); else asm volatile("s_waitcnt vmcnt(5)" ::: "memory"); }
;     else wait_vm0();
;     __syncthreads();
;     const char* s = lds + cur * STAGE;
;     const int nbuf = cur == 0 ? 2 : cur - 1;
;     const bool more = kt + 2 < nk;
;     half8 af[2][MB], bf[2][2];
; #pragma unroll
;     for (int mb = 0; mb < MB; ++mb) af[0][mb] = *(const half8*)(s + a_rd + mb * 4096 + (((0 + hh) ^ sw) * 16));
; #pragma unroll
;     for (int nb = 0; nb < 2; ++nb) bf[0][nb] = *(const half8*)(s + b_rd + nb * 4096 + (((0 + hh) ^ sw) * 16));
; #pragma unroll
;     for (int ks = 0; ks < 4; ++ks) {
;       if (ks < 3) {
; #pragma unroll
;         for (int mb = 0; mb < MB; ++mb) af[(ks + 1) & 1][mb] = *(const half8*)(s + a_rd + mb * 4096 + (((2 * (ks + 1) + hh) ^ sw) * 16));
; #pragma unroll
;         for (int nb = 0; nb < 2; ++nb) bf[(ks + 1) & 1][nb] = *(const half8*)(s + b_rd + nb * 4096 + (((2 * (ks + 1) + hh) ^ sw) * 16));
;       }
;       if (more) {
;         if (2 * ks < NP) piece(2 * ks, kt + 2, nbuf);
;         if (2 * ks + 1 < NP) piece(2 * ks + 1, kt + 2, nbuf);
;       }
;       __builtin_amdgcn_sched_barrier(0);
;       __builtin_amdgcn_s_setprio(1);
; #pragma unroll
;       for (int mb = 0; mb < MB; ++mb)
; #pragma unroll
;         for (int nb = 0; nb < 2; ++nb)
;           acc[mb][nb] = SWAP ? __builtin_amdgcn_mfma_f32_32x32x16_f16(bf[ks & 1][nb], af[ks & 1][mb], acc[mb][nb], 0, 0, 0)
;                              : __builtin_amdgcn_mfma_f32_32x32x16_f16(af[ks & 1][mb], bf[ks & 1][nb], acc[mb][nb], 0, 0, 0);
;       __builtin_amdgcn_s_setprio(0);
;       __builtin_amdgcn_sched_barrier(0);
;     }
.LBB0_40:
	s_mul_i32 s25, s24, 0xc000
	s_add_i32 s33, s25, 0
	s_add_i32 s25, s25, 0xffff4000
	s_cmp_lg_u32 s24, 0
	s_cselect_b32 s25, s25, 0x18000
	v_add_u32_e32 v51, s25, v10
	v_add_u32_e32 v11, s33, v6
	v_add_u32_e32 v50, s33, v4
	v_add_u32_e32 v48, 0x2000, v51
	v_lshl_add_u64 v[44:45], v[0:1], 0, s[80:81]
	v_readfirstlane_b32 s25, v51
	v_add_u32_e32 v16, v11, v9
	v_add_u32_e32 v24, v50, v9
	v_add_u32_e32 v32, v11, v8
	v_add_u32_e32 v40, v50, v8
	v_lshl_add_u64 v[46:47], v[44:45], 0, s[52:53]
	v_lshl_add_u64 v[44:45], v[44:45], 0, s[90:91]
	s_mov_b32 m0, s25
	v_readfirstlane_b32 s25, v48
	s_waitcnt vmcnt(6)
	s_waitcnt lgkmcnt(0)
	s_barrier
	ds_read_b128 v[12:15], v16
	ds_read_b128 v[16:19], v16 offset:4096
	ds_read_b128 v[20:23], v24 offset:16384
	ds_read_b128 v[24:27], v24 offset:20480
	ds_read_b128 v[28:31], v32
	ds_read_b128 v[32:35], v32 offset:4096
	ds_read_b128 v[36:39], v40 offset:16384
	ds_read_b128 v[40:43], v40 offset:20480
	global_load_lds_dwordx4 v[44:45], off
	s_mov_b32 m0, s25
	v_lshl_add_u64 v[44:45], v[2:3], 0, s[80:81]
	global_load_lds_dwordx4 v[46:47], off
	v_lshl_add_u64 v[46:47], v[44:45], 0, s[72:73]
	s_setprio 1
	s_waitcnt lgkmcnt(0)
	v_mfma_f32_32x32x16_f16 v[112:127], v[20:23], v[12:15], v[112:127]
	v_mfma_f32_32x32x16_f16 v[96:111], v[24:27], v[12:15], v[96:111]
	v_mfma_f32_32x32x16_f16 v[80:95], v[20:23], v[16:19], v[80:95]
	v_mfma_f32_32x32x16_f16 v[64:79], v[24:27], v[16:19], v[64:79]
	s_setprio 0
	v_add_u32_e32 v53, 0x4000, v51
	v_add_u32_e32 v52, 0x6000, v51
	v_readfirstlane_b32 s25, v53
	v_add_u32_e32 v16, v11, v7
	v_add_u32_e32 v24, v50, v7
	s_mov_b32 m0, s25
	v_readfirstlane_b32 s25, v52
	ds_read_b128 v[12:15], v16
	ds_read_b128 v[16:19], v16 offset:4096
	ds_read_b128 v[20:23], v24 offset:16384
	ds_read_b128 v[24:27], v24 offset:20480
	v_lshl_add_u64 v[48:49], v[44:45], 0, s[88:89]
	global_load_lds_dwordx4 v[46:47], off
	s_mov_b32 m0, s25
	s_nop 0
	global_load_lds_dwordx4 v[48:49], off
	s_setprio 1
	v_mfma_f32_32x32x16_f16 v[112:127], v[36:39], v[28:31], v[112:127]
	v_mfma_f32_32x32x16_f16 v[96:111], v[40:43], v[28:31], v[96:111]
	v_mfma_f32_32x32x16_f16 v[80:95], v[36:39], v[32:35], v[80:95]
	v_mfma_f32_32x32x16_f16 v[64:79], v[40:43], v[32:35], v[64:79]
	s_setprio 0
	v_add_u32_e32 v11, v11, v5
	ds_read_b128 v[28:31], v11
	ds_read_b128 v[32:35], v11 offset:4096
	v_add_u32_e32 v11, v50, v5
	v_add_u32_e32 v48, 0x8000, v51
	ds_read_b128 v[36:39], v11 offset:16384
	ds_read_b128 v[40:43], v11 offset:20480
	v_add_u32_e32 v11, 0xa000, v51
	v_readfirstlane_b32 s25, v48
	v_lshl_add_u64 v[46:47], v[44:45], 0, s[34:35]
	v_lshl_add_u64 v[44:45], v[44:45], 0, s[68:69]
	s_mov_b32 m0, s25
	v_readfirstlane_b32 s25, v11
	global_load_lds_dwordx4 v[44:45], off
	s_mov_b32 m0, s25
	s_nop 0
	global_load_lds_dwordx4 v[46:47], off
	s_setprio 1
	s_waitcnt lgkmcnt(0)
	v_mfma_f32_32x32x16_f16 v[112:127], v[20:23], v[12:15], v[112:127]
	v_mfma_f32_32x32x16_f16 v[96:111], v[24:27], v[12:15], v[96:111]
	v_mfma_f32_32x32x16_f16 v[80:95], v[20:23], v[16:19], v[80:95]
	v_mfma_f32_32x32x16_f16 v[64:79], v[24:27], v[16:19], v[64:79]
	s_setprio 0
	s_setprio 1
	v_mfma_f32_32x32x16_f16 v[112:127], v[36:39], v[28:31], v[112:127]
	v_mfma_f32_32x32x16_f16 v[96:111], v[40:43], v[28:31], v[96:111]
	v_mfma_f32_32x32x16_f16 v[80:95], v[36:39], v[32:35], v[80:95]
	v_mfma_f32_32x32x16_f16 v[64:79], v[40:43], v[32:35], v[64:79]
	s_setprio 0
	s_add_i32 s25, s24, 1
	s_cmp_lg_u32 s24, 2
	s_cselect_b32 s24, s25, 0
	s_add_u32 s80, s80, 0x80
	s_addc_u32 s81, s81, 0
	s_cmpk_eq_i32 s80, 0x700
	s_cbranch_scc0 .LBB0_40
	s_branch .Lstg40_join
	.p2align	6

; DI void wait_vm0() { asm volatile("s_waitcnt vmcnt(0)" ::: "memory"); }
; template <int MB, bool SWAP>
; DI void gemm_kloop(f32x16 (&acc)[MB][2], const h16* __restrict__ A, int lda, const h16* __restrict__ B, int ldb, int K, char* lds) {
;     ...
;   for (int kt = 0; kt < nk; ++kt) {
;     if (kt + 1 < nk) { if (MB == 2) asm volatile("s_waitcnt vmcnt(6)" ::: "memory"); else asm volatile("s_waitcnt vmcnt(5)" ::: "memory"); }
;     else wait_vm0();
;     __syncthreads();
;     const char* s = lds + cur * STAGE;
;     const int nbuf = cur == 0 ? 2 : cur - 1;
;     const bool more = kt + 2 < nk;
;     half8 af[2][MB], bf[2][2];
; #pragma unroll
;     for (int mb = 0; mb < MB; ++mb) af[0][mb] = *(const half8*)(s + a_rd + mb * 4096 + (((0 + hh) ^ sw) * 16));
; #pragma unroll
;     for (int nb = 0; nb < 2; ++nb) bf[0][nb] = *(const half8*)(s + b_rd + nb * 4096 + (((0 + hh) ^ sw) * 16));
; #pragma unroll
;     for (int ks = 0; ks < 4; ++ks) {
;       if (ks < 3) {
; #pragma unroll
;         for (int mb = 0; mb < MB; ++mb) af[(ks + 1) & 1][mb] = *(const half8*)(s + a_rd + mb * 4096 + (((2 * (ks + 1) + hh) ^ sw) * 16));
; #pragma unroll
;         for (int nb = 0; nb < 2; ++nb) bf[(ks + 1) & 1][nb] = *(const half8*)(s + b_rd + nb * 4096 + (((2 * (ks + 1) + hh) ^ sw) * 16));
;       }
;       if (more) {
;         if (2 * ks < NP) piece(2 * ks, kt + 2, nbuf);
;         if (2 * ks + 1 < NP) piece(2 * ks + 1, kt + 2, nbuf);
;       }
;       __builtin_amdgcn_sched_barrier(0);
;       __builtin_amdgcn_s_setprio(1);
; #pragma unroll
;       for (int mb = 0; mb < MB; ++mb)
; #pragma unroll
;         for (int nb = 0; nb < 2; ++nb)
;           acc[mb][nb] = SWAP ? __builtin_amdgcn_mfma_f32_32x32x16_f16(bf[ks & 1][nb], af[ks & 1][mb], acc[mb][nb], 0, 0, 0)
;                              : __builtin_amdgcn_mfma_f32_32x32x16_f16(af[ks & 1][mb], bf[ks & 1][nb], acc[mb][nb], 0, 0, 0);
;       __builtin_amdgcn_s_setprio(0);
;       __builtin_amdgcn_sched_barrier(0);
;     }
;     cur = cur == 2 ? 0 : cur + 1;
;   }
;   __syncthreads();
.Lstg40_join:
	s_cmp_eq_u32 s45, 1
	s_cselect_b32 s24, s12, 0x1ba66000
	s_cmp_lg_u32 s45, 0
	s_cselect_b32 s24, s24, 0x10f66000
	s_add_i32 s25, 0, 0x18000
	v_add_u32_e32 v38, s25, v6
	v_add_u32_e32 v10, v38, v9
	v_add3_u32 v18, s25, v9, v4
	v_add_u32_e32 v26, v38, v8
	v_add3_u32 v34, s25, v8, v4
	s_waitcnt vmcnt(6)
	s_waitcnt lgkmcnt(0)
	s_barrier
	ds_read_b128 v[0:3], v10
	ds_read_b128 v[10:13], v10 offset:4096
	ds_read_b128 v[14:17], v18 offset:16384
	ds_read_b128 v[18:21], v18 offset:20480
	ds_read_b128 v[22:25], v26
	ds_read_b128 v[26:29], v26 offset:4096
	ds_read_b128 v[30:33], v34 offset:16384
	ds_read_b128 v[34:37], v34 offset:20480
	s_mov_b32 vcc_hi, 0
	s_setprio 1
	s_waitcnt lgkmcnt(5)
	v_mfma_f32_32x32x16_f16 v[112:127], v[14:17], v[0:3], v[112:127]
	s_waitcnt lgkmcnt(4)
	v_mfma_f32_32x32x16_f16 v[96:111], v[18:21], v[0:3], v[96:111]
	v_mfma_f32_32x32x16_f16 v[80:95], v[14:17], v[10:13], v[80:95]
	v_mfma_f32_32x32x16_f16 v[64:79], v[18:21], v[10:13], v[64:79]
	s_setprio 0
	v_add_u32_e32 v10, v38, v7
	v_add3_u32 v18, s25, v7, v4
	ds_read_b128 v[0:3], v10
	ds_read_b128 v[10:13], v10 offset:4096
	ds_read_b128 v[14:17], v18 offset:16384
	ds_read_b128 v[18:21], v18 offset:20480
	s_setprio 1
	s_waitcnt lgkmcnt(5)
	v_mfma_f32_32x32x16_f16 v[112:127], v[30:33], v[22:25], v[112:127]
	s_waitcnt lgkmcnt(4)
	v_mfma_f32_32x32x16_f16 v[96:111], v[34:37], v[22:25], v[96:111]
	v_mfma_f32_32x32x16_f16 v[80:95], v[30:33], v[26:29], v[80:95]
	v_mfma_f32_32x32x16_f16 v[64:79], v[34:37], v[26:29], v[64:79]
	s_setprio 0
	v_add_u32_e32 v26, v38, v5
	v_add3_u32 v34, s25, v5, v4
	ds_read_b128 v[22:25], v26
	ds_read_b128 v[26:29], v26 offset:4096
	ds_read_b128 v[30:33], v34 offset:16384
	ds_read_b128 v[34:37], v34 offset:20480
	s_setprio 1
	s_waitcnt lgkmcnt(5)
	v_mfma_f32_32x32x16_f16 v[112:127], v[14:17], v[0:3], v[112:127]
	s_waitcnt lgkmcnt(4)
	v_mfma_f32_32x32x16_f16 v[96:111], v[18:21], v[0:3], v[96:111]
	v_mfma_f32_32x32x16_f16 v[80:95], v[14:17], v[10:13], v[80:95]
	v_mfma_f32_32x32x16_f16 v[64:79], v[18:21], v[10:13], v[64:79]
	s_setprio 0
	s_setprio 1
	s_waitcnt lgkmcnt(1)
	v_mfma_f32_32x32x16_f16 v[112:127], v[30:33], v[22:25], v[112:127]
	s_waitcnt lgkmcnt(0)
	v_mfma_f32_32x32x16_f16 v[96:111], v[34:37], v[22:25], v[96:111]
	v_mfma_f32_32x32x16_f16 v[80:95], v[30:33], v[26:29], v[80:95]
	v_mfma_f32_32x32x16_f16 v[64:79], v[34:37], v[26:29], v[64:79]
	s_setprio 0
	v_add_u32_e32 v6, 0, v6
	v_add_u32_e32 v4, 0, v4
	v_add_u32_e32 v10, v6, v9
	v_add_u32_e32 v9, v4, v9
	s_waitcnt vmcnt(0)
	s_barrier
	ds_read_b128 v[0:3], v10
	ds_read_b128 v[10:13], v10 offset:4096
	ds_read_b128 v[14:17], v9 offset:16384
	ds_read_b128 v[18:21], v9 offset:20480
	v_add_u32_e32 v9, v6, v8
	v_add_u32_e32 v8, v4, v8
	ds_read_b128 v[22:25], v9
	ds_read_b128 v[26:29], v9 offset:4096
	ds_read_b128 v[30:33], v8 offset:16384
	ds_read_b128 v[34:37], v8 offset:20480
	s_setprio 1
	s_waitcnt lgkmcnt(5)
	v_mfma_f32_32x32x16_f16 v[112:127], v[14:17], v[0:3], v[112:127]
	s_waitcnt lgkmcnt(4)
	v_mfma_f32_32x32x16_f16 v[96:111], v[18:21], v[0:3], v[96:111]
	v_mfma_f32_32x32x16_f16 v[80:95], v[14:17], v[10:13], v[80:95]
	v_mfma_f32_32x32x16_f16 v[64:79], v[18:21], v[10:13], v[64:79]
	s_setprio 0
	v_add_u32_e32 v8, v6, v7
	v_add_u32_e32 v7, v4, v7
	ds_read_b128 v[0:3], v8
	ds_read_b128 v[8:11], v8 offset:4096
	ds_read_b128 v[12:15], v7 offset:16384
	ds_read_b128 v[16:19], v7 offset:20480
	s_setprio 1
	s_waitcnt lgkmcnt(5)
	v_mfma_f32_32x32x16_f16 v[112:127], v[30:33], v[22:25], v[112:127]
	s_waitcnt lgkmcnt(4)
	v_mfma_f32_32x32x16_f16 v[96:111], v[34:37], v[22:25], v[96:111]
	v_mfma_f32_32x32x16_f16 v[80:95], v[30:33], v[26:29], v[80:95]
	v_mfma_f32_32x32x16_f16 v[64:79], v[34:37], v[26:29], v[64:79]
	s_setprio 0
	v_add_u32_e32 v6, v6, v5
	v_add_u32_e32 v28, v4, v5
	ds_read_b128 v[20:23], v6
	ds_read_b128 v[24:27], v6 offset:4096
	ds_read_b128 v[4:7], v28 offset:16384
	ds_read_b128 v[28:31], v28 offset:20480
	s_setprio 1
	s_waitcnt lgkmcnt(5)
	v_mfma_f32_32x32x16_f16 v[112:127], v[12:15], v[0:3], v[112:127]
	s_waitcnt lgkmcnt(4)
	v_mfma_f32_32x32x16_f16 v[96:111], v[16:19], v[0:3], v[96:111]
	v_mfma_f32_32x32x16_f16 v[80:95], v[12:15], v[8:11], v[80:95]
	v_mfma_f32_32x32x16_f16 v[64:79], v[16:19], v[8:11], v[64:79]
	s_setprio 0
	s_setprio 1
	s_waitcnt lgkmcnt(1)
	v_mfma_f32_32x32x16_f16 v[112:127], v[4:7], v[20:23], v[112:127]
	s_waitcnt lgkmcnt(0)
	v_mfma_f32_32x32x16_f16 v[96:111], v[28:31], v[20:23], v[96:111]
	v_mfma_f32_32x32x16_f16 v[80:95], v[4:7], v[24:27], v[80:95]
	v_mfma_f32_32x32x16_f16 v[64:79], v[28:31], v[24:27], v[64:79]
	s_setprio 0
	v_mov_b32_e32 v6, v208
	s_barrier
; DI void wait_vm0() { asm volatile("s_waitcnt vmcnt(0)" ::: "memory"); }
; DI int otid() { int t = threadIdx.x; asm volatile("" : "+v"(t)); return t; }
; template <int MB, bool SWAP>
; DI void gemm_kloop(f32x16 (&acc)[MB][2], const h16* __restrict__ A, int lda, const h16* __restrict__ B, int ldb, int K, char* lds) {
;     ...
;   const int tid = otid(), w = tid >> 6, lane = tid & 63;
;   const int wr = w >> 2, wc = w & 3;
;   const int lrow = w * 8 + (lane >> 3), pch = lane & 7;
;   const int gch = pch ^ ((lrow >> 1) & 7);
;   const unsigned voa = (unsigned)(lrow * lda + gch * 8) * 2u, vob = (unsigned)(lrow * ldb + gch * 8) * 2u;
;   const int lofs = lrow * 128 + pch * 16;
;   const int r32 = lane & 31, hh = lane >> 5, sw = (r32 >> 1) & 7;
;   const int a_rd = (wr * 32 * MB + r32) * 128;
;   const int b_rd = A_BYTES + (wc * 64 + r32) * 128;
;   const int nk = K >> 6;
;   constexpr int NP = MB + 4;
;   auto piece = [&](int p, int kt, int buf) {
;     char* s = lds + buf * STAGE;
;     if (p < MB) __builtin_amdgcn_global_load_lds((const unsigned*)((const char*)(A + (size_t)p * 64 * lda + kt * 64) + voa), (unsigned*)(s + p * 8192 + lofs), 16, 0, 0);
;     else __builtin_amdgcn_global_load_lds((const unsigned*)((const char*)(B + (size_t)(p - MB) * 64 * ldb + kt * 64) + vob), (unsigned*)(s + A_BYTES + (p - MB) * 8192 + lofs), 16, 0, 0);
;   };
;   wait_vm0();
; #pragma unroll
;   for (int p = 0; p < NP; ++p) piece(p, 0, 0);
; #pragma unroll
;   for (int p = 0; p < NP; ++p) piece(p, 1, 1);
; template <int MB>
; DI void merge_tile(const Params& P, int layer, size_t row0, int nt, char* smem) {
;     ...
;     zero_acc<MB>(pa2);
;     gemm_kloop<MB, true>(pa2, yn + row0 * LDY, LDY, wbrT + (size_t)(n * 1024 + nt * 256) * LDY, LDY, WB, smem);
	s_add_u32 s52, s3, s24
	v_ashrrev_i32_e32 v7, 3, v6
	v_bfe_u32 v8, v6, 3, 3
	v_and_or_b32 v0, v7, -8, v8
	v_lshrrev_b32_e32 v1, 1, v0
	v_xor_b32_e32 v1, v1, v6
	v_lshlrev_b32_e32 v1, 3, v1
	v_mul_lo_u32 v2, v0, s13
	v_and_b32_e32 v9, 56, v1
	v_or_b32_e32 v1, v9, v2
	v_lshlrev_b32_e32 v128, 1, v1
	v_lshlrev_b32_e32 v1, 4, v6
	v_and_b32_e32 v1, 0x70, v1
	v_lshl_or_b32 v10, v0, 7, v1
	s_addc_u32 s53, s2, 0
	s_or_b32 s25, vcc_lo, s71
	v_add_u32_e32 v205, 0, v10
	s_mul_i32 s84, s25, 0x240
	v_readfirstlane_b32 s25, v205
	s_nop 0
	s_mov_b32 m0, s25
	v_add_u32_e32 v13, 0x2000, v205
	v_lshl_add_u64 v[2:3], s[52:53], 0, v[128:129]
	global_load_lds_dwordx4 v128, s[52:53]
	s_mov_b64 s[52:53], 0x12000
	v_readfirstlane_b32 s25, v13
	s_lshl_b64 s[54:55], s[84:85], 1
	v_lshl_add_u64 v[4:5], v[2:3], 0, s[52:53]
	s_mov_b32 m0, s25
	s_add_u32 s54, s75, s54
	v_and_b32_e32 v0, 31, v6
	v_lshrrev_b32_e32 v1, 2, v6
	global_load_lds_dwordx4 v[4:5], off
	v_add_u32_e32 v4, 0x4000, v205
	s_addc_u32 s55, s76, s55
	v_and_or_b32 v12, v1, s7, v0
	v_lshlrev_b32_e32 v0, 7, v6
	v_readfirstlane_b32 s25, v4
	v_add_u32_e32 v13, 0x6000, v205
	v_and_b32_e32 v199, 0x6f80, v0
	v_lshl_add_u64 v[0:1], s[54:55], 0, v[128:129]
	s_mov_b32 m0, s25
	v_readfirstlane_b32 s25, v13
	v_add_u32_e32 v13, 0x8000, v205
	global_load_lds_dwordx4 v128, s[54:55]
	v_lshl_add_u64 v[4:5], v[0:1], 0, s[52:53]
	s_mov_b32 m0, s25
	s_mov_b64 s[52:53], 0x24000
	v_readfirstlane_b32 s25, v13
	v_add_u32_e32 v13, 0xa000, v205
	global_load_lds_dwordx4 v[4:5], off
	v_lshl_add_u64 v[4:5], v[0:1], 0, s[52:53]
	s_mov_b32 m0, s25
	s_mov_b64 s[52:53], 0x36000
	v_readfirstlane_b32 s25, v13
	v_lshlrev_b32_e32 v204, 7, v12
	v_add_u32_e32 v12, 0xc000, v205
	global_load_lds_dwordx4 v[4:5], off
	v_lshl_add_u64 v[4:5], v[0:1], 0, s[52:53]
	s_mov_b32 m0, s25
	v_readfirstlane_b32 s25, v12
	global_load_lds_dwordx4 v[4:5], off
	v_lshl_add_u64 v[4:5], v[2:3], 0, s[22:23]
	s_mov_b32 m0, s25
	s_mov_b64 s[52:53], 0x12080
	global_load_lds_dwordx4 v[4:5], off
	v_add_u32_e32 v4, 0xe000, v205
	v_lshl_add_u64 v[2:3], v[2:3], 0, s[52:53]
	v_readfirstlane_b32 s25, v4
	v_add_u32_e32 v4, s8, v10
	s_mov_b32 m0, s25
	v_readfirstlane_b32 s25, v4
	v_add_u32_e32 v4, s9, v10
	global_load_lds_dwordx4 v[2:3], off
	v_lshl_add_u64 v[2:3], v[0:1], 0, s[22:23]
	s_mov_b32 m0, s25
	v_readfirstlane_b32 s25, v4
	v_add_u32_e32 v4, s79, v10
	global_load_lds_dwordx4 v[2:3], off
	v_lshl_add_u64 v[2:3], v[0:1], 0, s[52:53]
	s_mov_b32 m0, s25
	s_mov_b64 s[52:53], 0x24080
	v_readfirstlane_b32 s25, v4
	global_load_lds_dwordx4 v[2:3], off
	v_lshl_add_u64 v[2:3], v[0:1], 0, s[52:53]
	s_mov_b32 m0, s25
	s_mov_b64 s[52:53], 0x36080
	global_load_lds_dwordx4 v[2:3], off
	v_add_u32_e32 v2, s10, v10
	v_lshl_add_u64 v[0:1], v[0:1], 0, s[52:53]
	v_readfirstlane_b32 s25, v2
	s_mov_b32 m0, s25
	v_lshrrev_b32_e32 v11, 1, v6
	global_load_lds_dwordx4 v[0:1], off
	v_bfe_u32 v13, v6, 5, 1
	v_bfe_u32 v0, v6, 1, 3
	v_bitop3_b32 v1, v13, v11, 7 bitop3:0x78
	v_lshlrev_b32_e32 v203, 4, v1
	v_bitop3_b32 v1, v13, v0, 2 bitop3:0x36
	v_lshlrev_b32_e32 v202, 4, v1
	v_bitop3_b32 v1, v13, v0, 4 bitop3:0x36
	v_bitop3_b32 v0, v13, v0, 6 bitop3:0x36
	v_lshlrev_b32_e32 v200, 4, v0
	v_lshrrev_b32_e32 v0, 3, v7
	v_mul_lo_u32 v0, v0, s14
	v_mad_u32_u24 v0, v8, s13, v0
	v_or_b32_e32 v0, v0, v9
	s_add_u32 s24, s70, s24
	v_lshlrev_b32_e32 v128, 1, v0
	s_addc_u32 s25, s44, 0
	v_mov_b32_e32 v0, 0
	v_lshlrev_b32_e32 v201, 4, v1
	v_lshl_add_u64 v[186:187], s[24:25], 0, v[128:129]
	v_lshl_add_u64 v[188:189], s[40:41], 0, v[128:129]
	s_mov_b64 s[80:81], 0
	v_mov_b32_e32 v1, v0
	v_mov_b32_e32 v2, v0
	v_mov_b32_e32 v3, v0
	v_mov_b32_e32 v4, v0
	v_mov_b32_e32 v5, v0
	v_mov_b32_e32 v6, v0
	v_mov_b32_e32 v7, v0
	v_mov_b32_e32 v8, v0
	v_mov_b32_e32 v9, v0
	v_mov_b32_e32 v10, v0
	v_mov_b32_e32 v11, v0
	v_mov_b32_e32 v12, v0
	v_mov_b32_e32 v13, v0
	v_mov_b32_e32 v14, v0
	v_mov_b32_e32 v15, v0
	v_mov_b32_e32 v16, v0
	v_mov_b32_e32 v17, v0
	v_mov_b32_e32 v18, v0
	v_mov_b32_e32 v19, v0
	v_mov_b32_e32 v20, v0
	v_mov_b32_e32 v21, v0
	v_mov_b32_e32 v22, v0
	v_mov_b32_e32 v23, v0
	v_mov_b32_e32 v24, v0
	v_mov_b32_e32 v25, v0
	v_mov_b32_e32 v26, v0
	v_mov_b32_e32 v27, v0
	v_mov_b32_e32 v28, v0
	v_mov_b32_e32 v29, v0
	v_mov_b32_e32 v30, v0
	v_mov_b32_e32 v31, v0
	v_mov_b32_e32 v32, v0
	v_mov_b32_e32 v33, v0
	v_mov_b32_e32 v34, v0
	v_mov_b32_e32 v35, v0
	v_mov_b32_e32 v36, v0
	v_mov_b32_e32 v37, v0
	v_mov_b32_e32 v38, v0
	v_mov_b32_e32 v39, v0
	v_mov_b32_e32 v40, v0
	v_mov_b32_e32 v41, v0
	v_mov_b32_e32 v42, v0
	v_mov_b32_e32 v43, v0
	v_mov_b32_e32 v44, v0
	v_mov_b32_e32 v45, v0
	v_mov_b32_e32 v46, v0
	v_mov_b32_e32 v47, v0
	v_mov_b32_e32 v48, v0
	v_mov_b32_e32 v49, v0
	v_mov_b32_e32 v50, v0
	v_mov_b32_e32 v51, v0
	v_mov_b32_e32 v52, v0
	v_mov_b32_e32 v53, v0
	v_mov_b32_e32 v54, v0
	v_mov_b32_e32 v55, v0
	v_mov_b32_e32 v56, v0
	v_mov_b32_e32 v57, v0
	v_mov_b32_e32 v58, v0
	v_mov_b32_e32 v59, v0
	v_mov_b32_e32 v60, v0
	v_mov_b32_e32 v61, v0
	v_mov_b32_e32 v62, v0
	v_mov_b32_e32 v63, v0
	s_mov_b64 s[52:53], 0x1188100
	v_readfirstlane_b32 s25, v208
	s_nop 0
	s_lshr_b32 s25, s25, 8
	s_cmp_lg_u32 s25, 0
	s_cbranch_scc1 .Lstg42_top
	.p2align	6
; DI void wait_vm0() { asm volatile("s_waitcnt vmcnt(0)" ::: "memory"); }
; template <int MB, bool SWAP>
; DI void gemm_kloop(f32x16 (&acc)[MB][2], const h16* __restrict__ A, int lda, const h16* __restrict__ B, int ldb, int K, char* lds) {
;     ...
;   for (int kt = 0; kt < nk; ++kt) {
;     if (kt + 1 < nk) { if (MB == 2) asm volatile("s_waitcnt vmcnt(6)" ::: "memory"); else asm volatile("s_waitcnt vmcnt(5)" ::: "memory"); }
;     else wait_vm0();
;     __syncthreads();
;     const char* s = lds + cur * STAGE;
;     const int nbuf = cur == 0 ? 2 : cur - 1;
;     const bool more = kt + 2 < nk;
;     half8 af[2][MB], bf[2][2];
; #pragma unroll
;     for (int mb = 0; mb < MB; ++mb) af[0][mb] = *(const half8*)(s + a_rd + mb * 4096 + (((0 + hh) ^ sw) * 16));
; #pragma unroll
;     for (int nb = 0; nb < 2; ++nb) bf[0][nb] = *(const half8*)(s + b_rd + nb * 4096 + (((0 + hh) ^ sw) * 16));
; #pragma unroll
;     for (int ks = 0; ks < 4; ++ks) {
;       if (ks < 3) {
; #pragma unroll
;         for (int mb = 0; mb < MB; ++mb) af[(ks + 1) & 1][mb] = *(const half8*)(s + a_rd + mb * 4096 + (((2 * (ks + 1) + hh) ^ sw) * 16));
; #pragma unroll
;         for (int nb = 0; nb < 2; ++nb) bf[(ks + 1) & 1][nb] = *(const half8*)(s + b_rd + nb * 4096 + (((2 * (ks + 1) + hh) ^ sw) * 16));
;       }
;       if (more) {
;         if (2 * ks < NP) piece(2 * ks, kt + 2, nbuf);
;         if (2 * ks + 1 < NP) piece(2 * ks + 1, kt + 2, nbuf);
;       }
;       __builtin_amdgcn_sched_barrier(0);
;       __builtin_amdgcn_s_setprio(1);
; #pragma unroll
;       for (int mb = 0; mb < MB; ++mb)
; #pragma unroll
;         for (int nb = 0; nb < 2; ++nb)
;           acc[mb][nb] = SWAP ? __builtin_amdgcn_mfma_f32_32x32x16_f16(bf[ks & 1][nb], af[ks & 1][mb], acc[mb][nb], 0, 0, 0)
;                              : __builtin_amdgcn_mfma_f32_32x32x16_f16(af[ks & 1][mb], bf[ks & 1][nb], acc[mb][nb], 0, 0, 0);
;       __builtin_amdgcn_s_setprio(0);
;       __builtin_amdgcn_sched_barrier(0);
;     }
.LBB0_42:
	s_mul_i32 s24, vcc_hi, 0xc000
	s_add_i32 s25, s24, 0
	v_add_u32_e32 v128, s25, v204
	v_add_u32_e32 v206, v128, v203
	v_add_u32_e32 v215, s25, v199
	s_add_i32 s24, s24, 0xffff4000
	s_waitcnt vmcnt(6)
	s_waitcnt lgkmcnt(0)
	s_barrier
	ds_read_b128 v[210:213], v206
	ds_read_b128 v[224:227], v206 offset:4096
	v_add_u32_e32 v206, v215, v203
	s_cmp_lg_u32 vcc_hi, 0
	ds_read_b128 v[228:231], v206 offset:16384
	ds_read_b128 v[232:235], v206 offset:20480
	s_cselect_b32 s24, s24, 0x18000
	v_add_u32_e32 v206, v128, v202
	ds_read_b128 v[236:239], v206
	ds_read_b128 v[240:243], v206 offset:4096
	v_add_u32_e32 v206, v215, v202
	v_add_u32_e32 v218, s24, v205
	ds_read_b128 v[244:247], v206 offset:16384
	ds_read_b128 v[248:251], v206 offset:20480
	v_add_u32_e32 v220, 0x2000, v218
	v_lshl_add_u64 v[206:207], v[186:187], 0, s[80:81]
	v_readfirstlane_b32 s24, v218
	v_lshl_add_u64 v[216:217], v[206:207], 0, s[92:93]
	v_lshl_add_u64 v[206:207], v[206:207], 0, s[30:31]
	s_mov_b32 m0, s24
	v_readfirstlane_b32 s24, v220
	global_load_lds_dwordx4 v[206:207], off
	s_mov_b32 m0, s24
	v_lshl_add_u64 v[206:207], v[188:189], 0, s[80:81]
	global_load_lds_dwordx4 v[216:217], off
	v_lshl_add_u64 v[216:217], v[206:207], 0, s[52:53]
	s_setprio 1
	s_waitcnt lgkmcnt(0)
	v_mfma_f32_32x32x16_f16 v[48:63], v[228:231], v[210:213], v[48:63]
	v_mfma_f32_32x32x16_f16 v[32:47], v[232:235], v[210:213], v[32:47]
	v_mfma_f32_32x32x16_f16 v[16:31], v[228:231], v[224:227], v[16:31]
	v_mfma_f32_32x32x16_f16 v[0:15], v[232:235], v[224:227], v[0:15]
	s_setprio 0
	v_add_u32_e32 v252, 0x4000, v218
	v_add_u32_e32 v220, v128, v201
	v_add_u32_e32 v223, 0x6000, v218
	v_readfirstlane_b32 s24, v252
	ds_read_b128 v[210:213], v220
	ds_read_b128 v[224:227], v220 offset:4096
	v_add_u32_e32 v220, v215, v201
	s_mov_b32 m0, s24
	v_readfirstlane_b32 s24, v223
	ds_read_b128 v[228:231], v220 offset:16384
	ds_read_b128 v[232:235], v220 offset:20480
	v_lshl_add_u64 v[220:221], v[206:207], 0, s[82:83]
	global_load_lds_dwordx4 v[216:217], off
	s_mov_b32 m0, s24
	s_nop 0
	global_load_lds_dwordx4 v[220:221], off
	s_setprio 1
	v_mfma_f32_32x32x16_f16 v[48:63], v[244:247], v[236:239], v[48:63]
	v_mfma_f32_32x32x16_f16 v[32:47], v[248:251], v[236:239], v[32:47]
	v_mfma_f32_32x32x16_f16 v[16:31], v[244:247], v[240:243], v[16:31]
	v_mfma_f32_32x32x16_f16 v[0:15], v[248:251], v[240:243], v[0:15]
	s_setprio 0
	v_add_u32_e32 v128, v128, v200
	ds_read_b128 v[236:239], v128
	ds_read_b128 v[240:243], v128 offset:4096
	v_add_u32_e32 v128, v215, v200
	v_add_u32_e32 v215, 0x8000, v218
	ds_read_b128 v[244:247], v128 offset:16384
	ds_read_b128 v[248:251], v128 offset:20480
	v_add_u32_e32 v128, 0xa000, v218
	v_readfirstlane_b32 s24, v215
	v_lshl_add_u64 v[216:217], v[206:207], 0, s[26:27]
	v_lshl_add_u64 v[206:207], v[206:207], 0, s[20:21]
	s_mov_b32 m0, s24
	v_readfirstlane_b32 s24, v128
	global_load_lds_dwordx4 v[206:207], off
	s_mov_b32 m0, s24
	s_nop 0
	global_load_lds_dwordx4 v[216:217], off
	s_setprio 1
	s_waitcnt lgkmcnt(0)
	v_mfma_f32_32x32x16_f16 v[48:63], v[228:231], v[210:213], v[48:63]
	v_mfma_f32_32x32x16_f16 v[32:47], v[232:235], v[210:213], v[32:47]
	v_mfma_f32_32x32x16_f16 v[16:31], v[228:231], v[224:227], v[16:31]
	v_mfma_f32_32x32x16_f16 v[0:15], v[232:235], v[224:227], v[0:15]
	s_setprio 0
	s_setprio 1
	v_mfma_f32_32x32x16_f16 v[48:63], v[244:247], v[236:239], v[48:63]
	v_mfma_f32_32x32x16_f16 v[32:47], v[248:251], v[236:239], v[32:47]
	v_mfma_f32_32x32x16_f16 v[16:31], v[244:247], v[240:243], v[16:31]
	v_mfma_f32_32x32x16_f16 v[0:15], v[248:251], v[240:243], v[0:15]
	s_setprio 0
	s_add_i32 s24, vcc_hi, 1
	s_cmp_lg_u32 vcc_hi, 2
	s_cselect_b32 vcc_hi, s24, 0
	s_add_u32 s80, s80, 0x80
	s_addc_u32 s81, s81, 0
	s_cmpk_eq_i32 s80, 0x300
	s_cbranch_scc0 .LBB0_42
	s_branch .Lstg42_join
	.p2align	6

; template <bool HEADPERM, class Sched, class Epi>
; DI void gemm256_stream(char* lds, const h16* __restrict__ Ab, int lda, const h16* __restrict__ Bb, int ldb, int K, const Sched& S, const Epi& E) {
;     ...
;   f32x4 acc[2][2][4][2];
; #pragma unroll
;   for (int a = 0; a < 2; ++a)
; #pragma unroll
;     for (int b = 0; b < 2; ++b)
; #pragma unroll
;       for (int m = 0; m < 4; ++m)
; #pragma unroll
;         for (int n = 0; n < 2; ++n) acc[a][b][m][n] = f32x4{0.f, 0.f, 0.f, 0.f};
.LBB0_161:
	s_add_u32 s74, s2, 0x100
	v_mov_b32_e32 v0, 0
	s_addc_u32 s80, s3, 0
	s_mov_b32 s81, -2
	v_mov_b32_e32 v1, v0
	v_mov_b32_e32 v2, v0
	v_mov_b32_e32 v3, v0
	v_mov_b32_e32 v4, v0
	v_mov_b32_e32 v5, v0
	v_mov_b32_e32 v6, v0
	v_mov_b32_e32 v7, v0
	v_mov_b32_e32 v16, v0
	v_mov_b32_e32 v17, v0
	v_mov_b32_e32 v18, v0
	v_mov_b32_e32 v19, v0
	v_mov_b32_e32 v20, v0
	v_mov_b32_e32 v21, v0
	v_mov_b32_e32 v22, v0
	v_mov_b32_e32 v23, v0
	v_mov_b32_e32 v32, v0
	v_mov_b32_e32 v33, v0
	v_mov_b32_e32 v34, v0
	v_mov_b32_e32 v35, v0
	v_mov_b32_e32 v36, v0
	v_mov_b32_e32 v37, v0
	v_mov_b32_e32 v38, v0
	v_mov_b32_e32 v39, v0
	v_mov_b32_e32 v48, v0
	v_mov_b32_e32 v49, v0
	v_mov_b32_e32 v50, v0
	v_mov_b32_e32 v51, v0
	v_mov_b32_e32 v52, v0
	v_mov_b32_e32 v53, v0
	v_mov_b32_e32 v54, v0
	v_mov_b32_e32 v55, v0
	v_mov_b32_e32 v8, v0
	v_mov_b32_e32 v9, v0
	v_mov_b32_e32 v10, v0
	v_mov_b32_e32 v11, v0
	v_mov_b32_e32 v12, v0
	v_mov_b32_e32 v13, v0
	v_mov_b32_e32 v14, v0
	v_mov_b32_e32 v15, v0
	v_mov_b32_e32 v24, v0
	v_mov_b32_e32 v25, v0
	v_mov_b32_e32 v26, v0
	v_mov_b32_e32 v27, v0
	v_mov_b32_e32 v28, v0
	v_mov_b32_e32 v29, v0
	v_mov_b32_e32 v30, v0
	v_mov_b32_e32 v31, v0
	v_mov_b32_e32 v40, v0
	v_mov_b32_e32 v41, v0
	v_mov_b32_e32 v42, v0
	v_mov_b32_e32 v43, v0
	v_mov_b32_e32 v44, v0
	v_mov_b32_e32 v45, v0
	v_mov_b32_e32 v46, v0
	v_mov_b32_e32 v47, v0
	v_mov_b32_e32 v56, v0
	v_mov_b32_e32 v57, v0
	v_mov_b32_e32 v58, v0
	v_mov_b32_e32 v59, v0
	v_mov_b32_e32 v60, v0
	v_mov_b32_e32 v61, v0
	v_mov_b32_e32 v62, v0
	v_mov_b32_e32 v63, v0
	v_mov_b32_e32 v64, v0
	v_mov_b32_e32 v65, v0
	v_mov_b32_e32 v66, v0
	v_mov_b32_e32 v67, v0
	v_mov_b32_e32 v68, v0
	v_mov_b32_e32 v69, v0
	v_mov_b32_e32 v70, v0
	v_mov_b32_e32 v71, v0
	v_mov_b32_e32 v80, v0
	v_mov_b32_e32 v81, v0
	v_mov_b32_e32 v82, v0
	v_mov_b32_e32 v83, v0
	v_mov_b32_e32 v84, v0
	v_mov_b32_e32 v85, v0
	v_mov_b32_e32 v86, v0
	v_mov_b32_e32 v87, v0
	v_mov_b32_e32 v96, v0
	v_mov_b32_e32 v97, v0
	v_mov_b32_e32 v98, v0
	v_mov_b32_e32 v99, v0
	v_mov_b32_e32 v100, v0
	v_mov_b32_e32 v101, v0
	v_mov_b32_e32 v102, v0
	v_mov_b32_e32 v103, v0
	v_mov_b32_e32 v112, v0
	v_mov_b32_e32 v113, v0
	v_mov_b32_e32 v114, v0
	v_mov_b32_e32 v115, v0
	v_mov_b32_e32 v116, v0
	v_mov_b32_e32 v117, v0
	v_mov_b32_e32 v118, v0
	v_mov_b32_e32 v119, v0
	v_mov_b32_e32 v72, v0
	v_mov_b32_e32 v73, v0
	v_mov_b32_e32 v74, v0
	v_mov_b32_e32 v75, v0
	v_mov_b32_e32 v76, v0
	v_mov_b32_e32 v77, v0
	v_mov_b32_e32 v78, v0
	v_mov_b32_e32 v79, v0
	v_mov_b32_e32 v88, v0
	v_mov_b32_e32 v89, v0
	v_mov_b32_e32 v90, v0
	v_mov_b32_e32 v91, v0
	v_mov_b32_e32 v92, v0
	v_mov_b32_e32 v93, v0
	v_mov_b32_e32 v94, v0
	v_mov_b32_e32 v95, v0
	v_mov_b32_e32 v104, v0
	v_mov_b32_e32 v105, v0
	v_mov_b32_e32 v106, v0
	v_mov_b32_e32 v107, v0
	v_mov_b32_e32 v108, v0
	v_mov_b32_e32 v109, v0
	v_mov_b32_e32 v110, v0
	v_mov_b32_e32 v111, v0
	v_mov_b32_e32 v120, v0
	v_mov_b32_e32 v121, v0
	v_mov_b32_e32 v122, v0
	v_mov_b32_e32 v123, v0
	v_mov_b32_e32 v124, v0
	v_mov_b32_e32 v125, v0
	v_mov_b32_e32 v126, v0
	v_mov_b32_e32 v127, v0
	.p2align	6

; template <int MODE, int TB>
; DI void toeplitz_task(const Params& P, int layer, int set, int cg, int chunk, char* smem) {
;     ...
;   const float invs = ((const float*)(P.ws + WS_INVS))[(set * 2 + MODE) * 512 + c];
;   const float bias = P.hbias[(layer * 2 + MODE) * 512 + c];
;   const int nsteps = (L >> 5) + 1;
;   constexpr int GS = TB == 4 ? 2 : 5;
;   const int ngroups = (nsteps + GS - 1) / GS;
;   const int npass = (TB == 4 || set) ? 1 : 2;
;   const h16* krw = krs + w * KLEN;
;   for (int pass = 0; pass < npass; ++pass) {
;     const int tb = chunk * 512 + pass * 256;
;     f32x4 acc[TB][8];
; #pragma unroll
;     for (int ta = 0; ta < TB; ++ta)
; #pragma unroll
;       for (int r = 0; r < 8; ++r) acc[ta][r] = f32x4{0.f, 0.f, 0.f, 0.f};
;     u32x4 cur[2 * GS], nxt[2 * GS];
;     auto load_group = [&](int g, u32x4 (&dst)[2 * GS]) {
; #pragma unroll
;       for (int q = 0; q < GS; ++q) {
;         const int s = -32 + (g * GS + q) * 32 + 8 * kg;
;         const int s2 = s + 8;
;         const int sc = min(max(s, 0), L - 8), sc2 = min(max(s2, 0), L - 8);
;         dst[2 * q] = *(const u32x4*)(Urow + sc);
;         dst[2 * q + 1] = *(const u32x4*)(Urow + sc2);
;       }
;     };
;     load_group(0, cur);
;     const int abase = OFF - tb - 8 * ((lane & 15) - kg);
;     half8 afn[TB];
; #pragma unroll
;     for (int ta = 0; ta < TB; ++ta) afn[ta] = *(const half8*)(krw + abase - 32 - 128 * ta);
;     for (int g = 0; g < ngroups; ++g) {
;       load_group(g + 1 < ngroups ? g + 1 : g, nxt);
;       __builtin_amdgcn_sched_barrier(0);
; #pragma unroll
;       for (int q = 0; q < GS; ++q) {
;         const int s0 = -32 + (g * GS + q) * 32;
;         half8 af[TB];
; #pragma unroll
;         for (int ta = 0; ta < TB; ++ta) { af[ta] = afn[ta]; afn[ta] = *(const half8*)(krw + abase + s0 + 32 - 128 * ta); }
;         unsigned d[8];
;         {
;           const int sw0 = s0 + 8 * kg, sw1 = sw0 + 8;
;           const bool va = (sw0 >= 0) && (sw0 < L), vb = (sw1 >= 0) && (sw1 < L);
; #pragma unroll
;           for (int e = 0; e < 4; ++e) { d[e] = va ? cur[2 * q][e] : 0u; d[4 + e] = vb ? cur[2 * q + 1][e] : 0u; }
;         }
; #pragma unroll
;         for (int r = 0; r < 8; ++r) {
;           u32x4 bw;
; #pragma unroll
;           for (int e = 0; e < 4; ++e)
.LBB0_403:
	s_or_b64 exec, exec, s[2:3]
	v_ashrrev_i32_e32 v158, 6, v157
	v_add_u32_e32 v152, s38, v158
	v_and_b32_e32 v160, 15, v157
	v_lshl_add_u32 v0, v160, 9, v152
	v_ashrrev_i32_e32 v1, 31, v0
	v_readlane_b32 s2, v253, 35
	v_readlane_b32 s52, v253, 1
	v_lshlrev_b64 v[142:143], 12, v[0:1]
	v_readlane_b32 s3, v253, 36
	v_ashrrev_i32_e32 v153, 31, v152
	v_readlane_b32 s66, v253, 15
	v_readlane_b32 s67, v253, 16
	v_lshl_add_u64 v[150:151], s[2:3], 0, v[142:143]
	s_mov_b32 s2, 0x32e4000
	v_lshl_add_u64 v[0:1], v[152:153], 2, s[66:67]
	v_add_co_u32_e32 v0, vcc, s2, v0
	v_bfe_u32 v159, v157, 4, 2
	s_nop 0
	v_addc_co_u32_e32 v1, vcc, 0, v1, vcc
	s_waitcnt vmcnt(0) lgkmcnt(0)
	s_barrier
	v_readlane_b32 s54, v253, 3
	v_readlane_b32 s55, v253, 4
	global_load_dword v156, v[0:1], off offset:2048
	v_lshl_add_u64 v[0:1], v[152:153], 0, s[0:1]
	v_lshlrev_b32_e32 v128, 4, v159
	v_lshl_add_u64 v[0:1], v[0:1], 2, s[54:55]
	v_lshl_add_u64 v[8:9], v[150:151], 0, v[128:129]
	global_load_dword v153, v[0:1], off offset:2048
	global_load_dwordx4 v[12:15], v[150:151], off
	global_load_dwordx4 v[108:111], v[8:9], off offset:16
	global_load_dwordx4 v[64:67], v[8:9], off
	s_nop 0
	global_load_dwordx4 v[0:3], v[8:9], off offset:80
	global_load_dwordx4 v[16:19], v[8:9], off offset:64
	global_load_dwordx4 v[4:7], v[8:9], off offset:144
	s_nop 0
	global_load_dwordx4 v[8:11], v[8:9], off offset:128
	s_lshl_b32 s2, s45, 6
	v_sub_u32_e32 v20, v159, v160
	s_and_b32 s2, s2, 0x600
	v_lshlrev_b32_e32 v20, 3, v20
	v_subrev_u32_e32 v20, s2, v20
	v_mul_lo_u32 v148, v158, s11
	v_lshlrev_b32_e32 v20, 1, v20
	v_add3_u32 v162, 0, v148, v20
	ds_read_b128 v[20:23], v162 offset:4160
	ds_read_b128 v[24:27], v162 offset:3904
	ds_read_b128 v[28:31], v162 offset:3648
	ds_read_b128 v[32:35], v162 offset:3392
	v_mov_b32_e32 v216, 0xbab64f3b
	v_mov_b32_e32 v215, 0x3c0881c4
	v_readlane_b32 s53, v253, 2
	v_readlane_b32 s56, v253, 5
	v_readlane_b32 s57, v253, 6
	v_readlane_b32 s58, v253, 7
	v_readlane_b32 s59, v253, 8
	v_readlane_b32 s60, v253, 9
	v_readlane_b32 s61, v253, 10
	v_readlane_b32 s62, v253, 11
	v_readlane_b32 s63, v253, 12
	v_readlane_b32 s64, v253, 13
	v_readlane_b32 s65, v253, 14
	ds_read_b128 v[224:227], v162 offset:4224
	ds_read_b128 v[232:235], v162 offset:3968
	ds_read_b128 v[236:239], v162 offset:3712
	ds_read_b128 v[240:243], v162 offset:3456
	s_mov_b32 s84, s85
	s_mov_b32 s86, s85
	s_mov_b32 s87, s85
	v_mov_b64_e32 v[36:37], s[84:85]
	v_cmp_eq_u32_e32 vcc, 3, v159
	v_mov_b64_e32 v[38:39], s[86:87]
	v_mov_b32_e32 v80, v129
	s_waitcnt vmcnt(6)
	v_cndmask_b32_e32 v55, 0, v12, vcc
	s_waitcnt lgkmcnt(7)
	v_mfma_f32_16x16x32_f16 v[40:43], v[20:23], v[36:39], 0
	v_cndmask_b32_e32 v63, 0, v13, vcc
	v_alignbit_b32 v83, v63, v55, 16
	v_mov_b32_e32 v81, v129
	s_waitcnt lgkmcnt(6)
	v_mfma_f32_16x16x32_f16 v[44:47], v[24:27], v[36:39], 0
	v_mov_b32_e32 v60, v129
	v_mov_b32_e32 v61, v129
	v_mov_b32_e32 v62, v55
	s_waitcnt lgkmcnt(5)
	v_mfma_f32_16x16x32_f16 v[48:51], v[28:31], v[36:39], 0
	v_mov_b32_e32 v52, v129
	v_mov_b32_e32 v53, v129
	v_mov_b32_e32 v54, v129
	s_waitcnt lgkmcnt(4)
	v_mfma_f32_16x16x32_f16 v[56:59], v[32:35], v[36:39], 0
	v_lshlrev_b32_e32 v39, 16, v55
	v_mov_b32_e32 v36, v129
	v_mov_b32_e32 v37, v129
	v_mov_b32_e32 v38, v129
	v_mov_b32_e32 v82, v39
	v_mfma_f32_16x16x32_f16 v[134:137], v[20:23], v[60:63], 0
	v_cndmask_b32_e32 v99, 0, v14, vcc
	v_mov_b32_e32 v96, v129
	v_mov_b32_e32 v97, v55
	v_mfma_f32_16x16x32_f16 v[84:87], v[32:35], v[36:39], 0
	v_mov_b32_e32 v98, v63
	v_alignbit_b32 v107, v99, v63, 16
	v_cndmask_b32_e32 v12, 0, v15, vcc
	v_mfma_f32_16x16x32_f16 v[120:123], v[24:27], v[80:83], 0
	v_alignbit_b32 v15, v12, v99, 16
	v_mov_b32_e32 v12, v39
	v_mov_b32_e32 v13, v83
	v_mfma_f32_16x16x32_f16 v[88:91], v[20:23], v[52:55], 0
	v_mov_b32_e32 v14, v107
	s_waitcnt vmcnt(4)
; template <int MODE, int TB>
; DI void toeplitz_task(const Params& P, int layer, int set, int cg, int chunk, char* smem) {
;     ...
;     for (int g = 0; g < ngroups; ++g) {
;       load_group(g + 1 < ngroups ? g + 1 : g, nxt);
;       __builtin_amdgcn_sched_barrier(0);
; #pragma unroll
;       for (int q = 0; q < GS; ++q) {
;         const int s0 = -32 + (g * GS + q) * 32;
;         half8 af[TB];
; #pragma unroll
;         for (int ta = 0; ta < TB; ++ta) { af[ta] = afn[ta]; afn[ta] = *(const half8*)(krw + abase + s0 + 32 - 128 * ta); }
;         unsigned d[8];
;         {
;           const int sw0 = s0 + 8 * kg, sw1 = sw0 + 8;
;           const bool va = (sw0 >= 0) && (sw0 < L), vb = (sw1 >= 0) && (sw1 < L);
; #pragma unroll
;           for (int e = 0; e < 4; ++e) { d[e] = va ? cur[2 * q][e] : 0u; d[4 + e] = vb ? cur[2 * q + 1][e] : 0u; }
;         }
; #pragma unroll
;         for (int r = 0; r < 8; ++r) {
;           u32x4 bw;
; #pragma unroll
;           for (int e = 0; e < 4; ++e)
;             bw[e] = (r & 1) ? __builtin_amdgcn_alignbit(d[(r >> 1) + e + 1 > 7 ? 7 : (r >> 1) + e + 1], d[(r >> 1) + e], 16) : d[(r >> 1) + e];
;           const half8 bfr = __builtin_bit_cast(half8, bw);
; #pragma unroll
;           for (int ta = 0; ta < TB; ++ta) acc[ta][r] = __builtin_amdgcn_mfma_f32_16x16x32_f16(af[ta], bfr, acc[ta][r], 0, 0, 0);
;         }
	v_perm_b32 v244, v64, v65, s29
	v_perm_b32 v245, v65, v66, s29
	v_mfma_f32_16x16x32_f16 v[92:95], v[24:27], v[52:55], 0
	v_perm_b32 v246, v66, v67, s29
	v_perm_b32 v247, v67, v108, s29
	v_mov_b32_e32 v104, v129
	v_mfma_f32_16x16x32_f16 v[100:103], v[28:31], v[52:55], 0
	v_mov_b32_e32 v105, v39
	v_mov_b32_e32 v106, v83
	v_perm_b32 v251, v108, v109, s29
	v_mfma_f32_16x16x32_f16 v[112:115], v[32:35], v[52:55], 0
	v_mov_b32_e32 v248, v245
	v_mov_b32_e32 v249, v246
	v_mov_b32_e32 v250, v247
	v_mfma_f32_16x16x32_f16 v[130:133], v[32:35], v[80:83], 0
	v_lshlrev_b32_e32 v161, 4, v160
	s_lshl_b32 s3, s45, 7
	s_and_b32 s3, s3, 0xc00
	v_mfma_f32_16x16x32_f16 v[144:147], v[28:31], v[60:63], 0
	v_readlane_b32 s24, v254, 43
	v_or_b32_e32 v142, v142, v128
	v_readlane_b32 s25, v254, 44
	v_mfma_f32_16x16x32_f16 v[184:187], v[20:23], v[96:99], 0
	s_nop 0
	v_lshl_add_u64 v[154:155], s[24:25], 0, v[142:143]
	v_mfma_f32_16x16x32_f16 v[188:191], v[24:27], v[96:99], 0
	v_mfma_f32_16x16x32_f16 v[192:195], v[28:31], v[96:99], 0
	v_mfma_f32_16x16x32_f16 v[196:199], v[32:35], v[96:99], 0
	v_mfma_f32_16x16x32_f16 v[116:119], v[20:23], v[80:83], 0
	v_mfma_f32_16x16x32_f16 v[138:141], v[24:27], v[60:63], 0
	v_mfma_f32_16x16x32_f16 v[68:71], v[20:23], v[36:39], 0
	v_mfma_f32_16x16x32_f16 v[72:75], v[24:27], v[36:39], 0
	v_mfma_f32_16x16x32_f16 v[76:79], v[28:31], v[36:39], 0
	v_mfma_f32_16x16x32_f16 v[124:127], v[28:31], v[80:83], 0
	v_mfma_f32_16x16x32_f16 v[164:167], v[32:35], v[60:63], 0
	v_mfma_f32_16x16x32_f16 v[200:203], v[20:23], v[12:15], 0
	v_mfma_f32_16x16x32_f16 v[204:207], v[24:27], v[12:15], 0
	v_mfma_f32_16x16x32_f16 v[210:213], v[28:31], v[12:15], 0
	v_mfma_f32_16x16x32_f16 v[228:231], v[32:35], v[12:15], 0
	s_waitcnt lgkmcnt(3)
	v_mfma_f32_16x16x32_f16 v[12:15], v[224:227], v[64:67], v[40:43]
	s_waitcnt lgkmcnt(2)
	v_mfma_f32_16x16x32_f16 v[36:39], v[232:235], v[64:67], v[44:47]
	s_waitcnt lgkmcnt(1)
	v_mfma_f32_16x16x32_f16 v[60:63], v[236:239], v[64:67], v[48:51]
	s_waitcnt lgkmcnt(0)
	v_mfma_f32_16x16x32_f16 v[80:83], v[240:243], v[64:67], v[56:59]
	v_mfma_f32_16x16x32_f16 v[44:47], v[240:243], v[244:247], v[84:87]
	s_nop 2
	v_pk_mov_b32 v[86:87], v[66:67], v[108:109] op_sel:[1,0]
	v_pk_mov_b32 v[84:85], v[64:65], v[66:67] op_sel:[1,0]
	v_mov_b32_e32 v64, v66
	v_mov_b32_e32 v65, v67
	v_mov_b32_e32 v66, v108
	v_mov_b32_e32 v67, v109
	v_mfma_f32_16x16x32_f16 v[168:171], v[20:23], v[104:107], 0
	v_mfma_f32_16x16x32_f16 v[172:175], v[24:27], v[104:107], 0
	v_mfma_f32_16x16x32_f16 v[176:179], v[28:31], v[104:107], 0
	v_mfma_f32_16x16x32_f16 v[180:183], v[32:35], v[104:107], 0
	v_mfma_f32_16x16x32_f16 v[24:27], v[232:235], v[248:251], v[120:123]
	v_mfma_f32_16x16x32_f16 v[120:123], v[224:227], v[64:67], v[134:137]
	s_nop 2
	v_pk_mov_b32 v[136:137], v[108:109], v[110:111] op_sel:[1,0]
	v_mov_b32_e32 v134, v86
	v_mov_b32_e32 v135, v87
	v_mfma_f32_16x16x32_f16 v[104:107], v[224:227], v[84:87], v[88:91]
	v_mfma_f32_16x16x32_f16 v[96:99], v[232:235], v[84:87], v[92:95]
	v_mfma_f32_16x16x32_f16 v[88:91], v[236:239], v[84:87], v[100:103]
	v_mfma_f32_16x16x32_f16 v[40:43], v[240:243], v[84:87], v[112:115]
	v_mfma_f32_16x16x32_f16 v[32:35], v[240:243], v[248:251], v[130:133]
	v_mfma_f32_16x16x32_f16 v[112:115], v[236:239], v[64:67], v[144:147]
	s_nop 1
	v_perm_b32 v133, v109, v110, s29
	v_mov_b32_e32 v130, v246
	v_mov_b32_e32 v131, v247
	v_mfma_f32_16x16x32_f16 v[100:103], v[224:227], v[134:137], v[184:187]
	v_perm_b32 v147, v110, v111, s29
	v_mov_b32_e32 v132, v251
	v_mov_b32_e32 v144, v247
	v_mfma_f32_16x16x32_f16 v[92:95], v[232:235], v[134:137], v[188:191]
	v_mov_b32_e32 v145, v251
	v_mov_b32_e32 v146, v133
	v_mfma_f32_16x16x32_f16 v[84:87], v[236:239], v[134:137], v[192:195]
	v_mfma_f32_16x16x32_f16 v[108:111], v[240:243], v[134:137], v[196:199]
	v_or_b32_e32 v134, v148, v128
	v_mov_b32_e32 v148, 0x80
	v_mfma_f32_16x16x32_f16 v[28:31], v[224:227], v[248:251], v[116:119]
	v_mfma_f32_16x16x32_f16 v[116:119], v[232:235], v[64:67], v[138:141]
	s_nop 2
	v_sub_u32_e32 v138, v134, v161
	v_subrev_u32_e32 v138, s3, v138
	v_mfma_f32_16x16x32_f16 v[56:59], v[224:227], v[244:247], v[68:71]
	v_add_u32_e32 v163, 0, v138
	s_movk_i32 s3, 0xf080
	v_mfma_f32_16x16x32_f16 v[52:55], v[232:235], v[244:247], v[72:75]
	v_mfma_f32_16x16x32_f16 v[48:51], v[236:239], v[244:247], v[76:79]
	v_mfma_f32_16x16x32_f16 v[20:23], v[236:239], v[248:251], v[124:127]
	v_mfma_f32_16x16x32_f16 v[124:127], v[240:243], v[64:67], v[164:167]
	v_mfma_f32_16x16x32_f16 v[76:79], v[224:227], v[130:133], v[168:171]
	s_nop 1
	v_lshl_or_b32 v164, v159, 3, v148
	v_mfma_f32_16x16x32_f16 v[72:75], v[232:235], v[130:133], v[172:175]
	v_mfma_f32_16x16x32_f16 v[68:71], v[236:239], v[130:133], v[176:179]
	v_mfma_f32_16x16x32_f16 v[64:67], v[240:243], v[130:133], v[180:183]
	v_mfma_f32_16x16x32_f16 v[130:133], v[224:227], v[144:147], v[200:203]
	v_mfma_f32_16x16x32_f16 v[134:137], v[232:235], v[144:147], v[204:207]
	v_mfma_f32_16x16x32_f16 v[138:141], v[236:239], v[144:147], v[210:213]
	v_mfma_f32_16x16x32_f16 v[146:149], v[240:243], v[144:147], v[228:231]
	.p2align	6

; template <int MODE, int TB>
; DI void toeplitz_task(const Params& P, int layer, int set, int cg, int chunk, char* smem) {
;     ...
;   const float invs = ((const float*)(P.ws + WS_INVS))[(set * 2 + MODE) * 512 + c];
;   const float bias = P.hbias[(layer * 2 + MODE) * 512 + c];
;   const int nsteps = (L >> 5) + 1;
;   constexpr int GS = TB == 4 ? 2 : 5;
;   const int ngroups = (nsteps + GS - 1) / GS;
;   const int npass = (TB == 4 || set) ? 1 : 2;
;   const h16* krw = krs + w * KLEN;
;   for (int pass = 0; pass < npass; ++pass) {
;     const int tb = chunk * 512 + pass * 256;
;     f32x4 acc[TB][8];
; #pragma unroll
;     for (int ta = 0; ta < TB; ++ta)
; #pragma unroll
;       for (int r = 0; r < 8; ++r) acc[ta][r] = f32x4{0.f, 0.f, 0.f, 0.f};
;     u32x4 cur[2 * GS], nxt[2 * GS];
;     auto load_group = [&](int g, u32x4 (&dst)[2 * GS]) {
; #pragma unroll
;       for (int q = 0; q < GS; ++q) {
;         const int s = -32 + (g * GS + q) * 32 + 8 * kg;
;         const int s2 = s + 8;
;         const int sc = min(max(s, 0), L - 8), sc2 = min(max(s2, 0), L - 8);
;         dst[2 * q] = *(const u32x4*)(Urow + sc);
;         dst[2 * q + 1] = *(const u32x4*)(Urow + sc2);
;       }
;     };
;     load_group(0, cur);
;     const int abase = OFF - tb - 8 * ((lane & 15) - kg);
;     half8 afn[TB];
; #pragma unroll
;     for (int ta = 0; ta < TB; ++ta) afn[ta] = *(const half8*)(krw + abase - 32 - 128 * ta);
;     for (int g = 0; g < ngroups; ++g) {
;       load_group(g + 1 < ngroups ? g + 1 : g, nxt);
;       __builtin_amdgcn_sched_barrier(0);
; #pragma unroll
;       for (int q = 0; q < GS; ++q) {
;         const int s0 = -32 + (g * GS + q) * 32;
;         half8 af[TB];
; #pragma unroll
;         for (int ta = 0; ta < TB; ++ta) { af[ta] = afn[ta]; afn[ta] = *(const half8*)(krw + abase + s0 + 32 - 128 * ta); }
;         unsigned d[8];
;         {
;           const int sw0 = s0 + 8 * kg, sw1 = sw0 + 8;
;           const bool va = (sw0 >= 0) && (sw0 < L), vb = (sw1 >= 0) && (sw1 < L);
; #pragma unroll
;           for (int e = 0; e < 4; ++e) { d[e] = va ? cur[2 * q][e] : 0u; d[4 + e] = vb ? cur[2 * q + 1][e] : 0u; }
;         }
; #pragma unroll
;         for (int r = 0; r < 8; ++r) {
;           u32x4 bw;
; #pragma unroll
;           for (int e = 0; e < 4; ++e)
.LBB0_422:
	s_or_b64 exec, exec, s[0:1]
	v_ashrrev_i32_e32 v16, 6, v2
	v_and_b32_e32 v153, 15, v2
	v_add_u32_e32 v156, s24, v16
	v_lshlrev_b32_e32 v160, 11, v153
	v_add_u32_e32 v0, v160, v156
	v_readlane_b32 s0, v253, 51
	v_ashrrev_i32_e32 v1, 31, v0
	v_ashrrev_i32_e32 v157, 31, v156
	v_readlane_b32 s1, v253, 52
	v_lshlrev_b64 v[142:143], 12, v[0:1]
	s_waitcnt vmcnt(0) lgkmcnt(0)
	v_lshl_add_u64 v[0:1], v[156:157], 2, s[0:1]
	s_barrier
	v_bfe_u32 v151, v2, 4, 2
	global_load_dword v150, v[0:1], off
	v_add_u32_e32 v0, s41, v156
	v_readlane_b32 s52, v253, 1
	v_lshl_add_u64 v[154:155], s[48:49], 0, v[142:143]
	v_ashrrev_i32_e32 v1, 31, v0
	v_readlane_b32 s54, v253, 3
	v_readlane_b32 s55, v253, 4
	v_lshlrev_b32_e32 v128, 4, v151
	v_lshl_add_u64 v[8:9], v[154:155], 0, v[128:129]
	v_lshl_add_u64 v[0:1], v[0:1], 2, s[54:55]
	global_load_dword v152, v[0:1], off
	global_load_dwordx4 v[12:15], v[154:155], off
	global_load_dwordx4 v[104:107], v[8:9], off offset:16
	global_load_dwordx4 v[56:59], v[8:9], off
	s_nop 0
	global_load_dwordx4 v[0:3], v[8:9], off offset:80
	global_load_dwordx4 v[100:103], v[8:9], off offset:64
	global_load_dwordx4 v[4:7], v[8:9], off offset:144
	s_nop 0
	global_load_dwordx4 v[8:11], v[8:9], off offset:128
	v_mul_lo_u32 v148, v16, s11
	s_lshl_b32 s0, s42, 6
	v_sub_u32_e32 v16, v151, v153
	s_and_b32 s0, s0, 0x600
	v_lshlrev_b32_e32 v16, 3, v16
	v_subrev_u32_e32 v16, s0, v16
	v_lshlrev_b32_e32 v16, 1, v16
	v_add3_u32 v157, 0, v148, v16
	ds_read_b128 v[16:19], v157 offset:4160
	ds_read_b128 v[20:23], v157 offset:3904
	ds_read_b128 v[24:27], v157 offset:3648
	ds_read_b128 v[28:31], v157 offset:3392
	v_mov_b32_e32 v216, 0xbab64f3b
	v_mov_b32_e32 v215, 0x3c0881c4
	v_readlane_b32 s53, v253, 2
	v_readlane_b32 s56, v253, 5
	v_readlane_b32 s57, v253, 6
	v_readlane_b32 s58, v253, 7
	v_readlane_b32 s59, v253, 8
	v_readlane_b32 s60, v253, 9
	v_readlane_b32 s61, v253, 10
	v_readlane_b32 s62, v253, 11
	v_readlane_b32 s63, v253, 12
	v_readlane_b32 s64, v253, 13
	v_readlane_b32 s65, v253, 14
	v_readlane_b32 s66, v253, 15
	v_readlane_b32 s67, v253, 16
	ds_read_b128 v[228:231], v157 offset:4224
	ds_read_b128 v[236:239], v157 offset:3968
	ds_read_b128 v[240:243], v157 offset:3712
	ds_read_b128 v[244:247], v157 offset:3456
	s_mov_b32 s84, s85
	v_cmp_eq_u32_e32 vcc, 3, v151
	s_mov_b32 s86, s85
	s_mov_b32 s87, s85
	v_mov_b64_e32 v[32:33], s[84:85]
	s_waitcnt vmcnt(6)
	v_cndmask_b32_e32 v51, 0, v12, vcc
	v_mov_b64_e32 v[34:35], s[86:87]
	v_lshlrev_b32_e32 v55, 16, v51
	v_mov_b32_e32 v52, v129
	v_mov_b32_e32 v53, v129
	v_mov_b32_e32 v54, v129
	v_cndmask_b32_e32 v83, 0, v13, vcc
	s_waitcnt lgkmcnt(7)
	v_mfma_f32_16x16x32_f16 v[36:39], v[16:19], v[32:35], 0
	v_alignbit_b32 v91, v83, v51, 16
	v_mov_b32_e32 v88, v129
	v_mov_b32_e32 v89, v129
	s_waitcnt lgkmcnt(6)
	v_mfma_f32_16x16x32_f16 v[40:43], v[20:23], v[32:35], 0
	v_mov_b32_e32 v90, v55
	v_mov_b32_e32 v80, v129
	v_mov_b32_e32 v81, v129
	s_waitcnt lgkmcnt(5)
	v_mfma_f32_16x16x32_f16 v[44:47], v[24:27], v[32:35], 0
	v_mov_b32_e32 v82, v51
	v_mov_b32_e32 v48, v129
	v_mov_b32_e32 v49, v129
	s_waitcnt lgkmcnt(4)
	v_mfma_f32_16x16x32_f16 v[32:35], v[28:31], v[32:35], 0
	v_mov_b32_e32 v50, v129
	v_cndmask_b32_e32 v12, 0, v15, vcc
	v_mov_b32_e32 v96, v129
	v_mfma_f32_16x16x32_f16 v[68:71], v[24:27], v[52:55], 0
	v_mov_b32_e32 v97, v55
	v_mov_b32_e32 v98, v91
	v_mov_b32_e32 v13, v91
	v_mfma_f32_16x16x32_f16 v[72:75], v[28:31], v[52:55], 0
	s_waitcnt vmcnt(4)
	v_perm_b32 v248, v56, v57, s29
	v_perm_b32 v249, v57, v58, s29
	v_perm_b32 v250, v58, v59, s29
	v_mfma_f32_16x16x32_f16 v[60:63], v[16:19], v[52:55], 0
	v_perm_b32 v251, v59, v104, s29
	v_perm_b32 v213, v104, v105, s29
	v_mov_b32_e32 v210, v249
	v_mfma_f32_16x16x32_f16 v[64:67], v[20:23], v[52:55], 0
	v_cndmask_b32_e32 v53, 0, v14, vcc
	v_mov_b32_e32 v52, v83
	v_alignbit_b32 v99, v53, v83, 16
	v_mfma_f32_16x16x32_f16 v[116:119], v[20:23], v[88:91], 0
	v_alignbit_b32 v15, v12, v53, 16
	v_mov_b32_e32 v12, v55
	v_mov_b32_e32 v14, v99
	v_mfma_f32_16x16x32_f16 v[134:137], v[16:19], v[80:83], 0
	v_mov_b32_e32 v211, v250
	v_mov_b32_e32 v212, v251
	s_lshl_b32 s1, s42, 7
	v_mfma_f32_16x16x32_f16 v[76:79], v[16:19], v[48:51], 0
	s_and_b32 s1, s1, 0xc00
	v_readlane_b32 s2, v254, 45
	v_or_b32_e32 v142, v142, v128
	v_mfma_f32_16x16x32_f16 v[84:87], v[20:23], v[48:51], 0
	v_readlane_b32 s3, v254, 46
	v_mfma_f32_16x16x32_f16 v[92:95], v[24:27], v[48:51], 0
	s_nop 0
	v_lshl_add_u64 v[158:159], s[2:3], 0, v[142:143]
	v_mfma_f32_16x16x32_f16 v[108:111], v[28:31], v[48:51], 0
	v_mfma_f32_16x16x32_f16 v[130:133], v[28:31], v[88:91], 0
	v_mfma_f32_16x16x32_f16 v[144:147], v[24:27], v[80:83], 0
	v_mfma_f32_16x16x32_f16 v[182:185], v[16:19], v[50:53], 0
	v_mfma_f32_16x16x32_f16 v[186:189], v[20:23], v[50:53], 0
	v_mfma_f32_16x16x32_f16 v[190:193], v[24:27], v[50:53], 0
	v_mfma_f32_16x16x32_f16 v[194:197], v[28:31], v[50:53], 0
	v_mfma_f32_16x16x32_f16 v[112:115], v[16:19], v[88:91], 0
	v_mfma_f32_16x16x32_f16 v[138:141], v[20:23], v[80:83], 0
	v_mfma_f32_16x16x32_f16 v[162:165], v[28:31], v[80:83], 0
	v_mfma_f32_16x16x32_f16 v[178:181], v[28:31], v[96:99], 0
	v_mfma_f32_16x16x32_f16 v[232:235], v[28:31], v[12:15], 0
	s_waitcnt lgkmcnt(3)
; template <int MODE, int TB>
; DI void toeplitz_task(const Params& P, int layer, int set, int cg, int chunk, char* smem) {
;     ...
;     for (int g = 0; g < ngroups; ++g) {
;       load_group(g + 1 < ngroups ? g + 1 : g, nxt);
;       __builtin_amdgcn_sched_barrier(0);
; #pragma unroll
;       for (int q = 0; q < GS; ++q) {
;         const int s0 = -32 + (g * GS + q) * 32;
;         half8 af[TB];
; #pragma unroll
;         for (int ta = 0; ta < TB; ++ta) { af[ta] = afn[ta]; afn[ta] = *(const half8*)(krw + abase + s0 + 32 - 128 * ta); }
;         unsigned d[8];
;         {
;           const int sw0 = s0 + 8 * kg, sw1 = sw0 + 8;
;           const bool va = (sw0 >= 0) && (sw0 < L), vb = (sw1 >= 0) && (sw1 < L);
; #pragma unroll
;           for (int e = 0; e < 4; ++e) { d[e] = va ? cur[2 * q][e] : 0u; d[4 + e] = vb ? cur[2 * q + 1][e] : 0u; }
;         }
; #pragma unroll
;         for (int r = 0; r < 8; ++r) {
;           u32x4 bw;
; #pragma unroll
;           for (int e = 0; e < 4; ++e)
;             bw[e] = (r & 1) ? __builtin_amdgcn_alignbit(d[(r >> 1) + e + 1 > 7 ? 7 : (r >> 1) + e + 1], d[(r >> 1) + e], 16) : d[(r >> 1) + e];
;           const half8 bfr = __builtin_bit_cast(half8, bw);
; #pragma unroll
;           for (int ta = 0; ta < TB; ++ta) acc[ta][r] = __builtin_amdgcn_mfma_f32_16x16x32_f16(af[ta], bfr, acc[ta][r], 0, 0, 0);
;         }
	v_mfma_f32_16x16x32_f16 v[28:31], v[228:231], v[56:59], v[36:39]
	s_waitcnt lgkmcnt(2)
	v_mfma_f32_16x16x32_f16 v[52:55], v[236:239], v[56:59], v[40:43]
	s_waitcnt lgkmcnt(1)
	v_mfma_f32_16x16x32_f16 v[80:83], v[240:243], v[56:59], v[44:47]
	s_waitcnt lgkmcnt(0)
	v_mfma_f32_16x16x32_f16 v[124:127], v[244:247], v[56:59], v[32:35]
	v_mfma_f32_16x16x32_f16 v[40:43], v[240:243], v[248:251], v[68:71]
	v_mfma_f32_16x16x32_f16 v[36:39], v[244:247], v[248:251], v[72:75]
	s_nop 1
	v_pk_mov_b32 v[70:71], v[56:57], v[58:59] op_sel:[1,0]
	v_mov_b32_e32 v56, v58
	v_mov_b32_e32 v57, v59
	v_pk_mov_b32 v[72:73], v[58:59], v[104:105] op_sel:[1,0]
	v_mov_b32_e32 v58, v104
	v_mov_b32_e32 v59, v105
	v_mfma_f32_16x16x32_f16 v[120:123], v[24:27], v[88:91], 0
	v_mfma_f32_16x16x32_f16 v[166:169], v[16:19], v[96:99], 0
	v_mfma_f32_16x16x32_f16 v[170:173], v[20:23], v[96:99], 0
	v_mfma_f32_16x16x32_f16 v[174:177], v[24:27], v[96:99], 0
	v_mfma_f32_16x16x32_f16 v[198:201], v[16:19], v[12:15], 0
	v_mfma_f32_16x16x32_f16 v[202:205], v[20:23], v[12:15], 0
	v_mfma_f32_16x16x32_f16 v[224:227], v[24:27], v[12:15], 0
	v_mfma_f32_16x16x32_f16 v[16:19], v[236:239], v[210:213], v[116:119]
	v_mfma_f32_16x16x32_f16 v[116:119], v[228:231], v[56:59], v[134:137]
	s_nop 2
	v_pk_mov_b32 v[136:137], v[104:105], v[106:107] op_sel:[1,0]
	v_mov_b32_e32 v134, v72
	v_mov_b32_e32 v135, v73
	v_mfma_f32_16x16x32_f16 v[96:99], v[228:231], v[70:73], v[76:79]
	v_mfma_f32_16x16x32_f16 v[88:91], v[236:239], v[70:73], v[84:87]
	v_mfma_f32_16x16x32_f16 v[76:79], v[240:243], v[70:73], v[92:95]
	v_mfma_f32_16x16x32_f16 v[32:35], v[244:247], v[70:73], v[108:111]
	v_mfma_f32_16x16x32_f16 v[24:27], v[244:247], v[210:213], v[130:133]
	v_mfma_f32_16x16x32_f16 v[108:111], v[240:243], v[56:59], v[144:147]
	s_nop 1
	v_perm_b32 v133, v105, v106, s29
	v_mov_b32_e32 v130, v250
	v_mov_b32_e32 v131, v251
	v_mfma_f32_16x16x32_f16 v[92:95], v[228:231], v[134:137], v[182:185]
	v_perm_b32 v147, v106, v107, s29
	v_mov_b32_e32 v132, v213
	v_mov_b32_e32 v144, v251
	v_mfma_f32_16x16x32_f16 v[84:87], v[236:239], v[134:137], v[186:189]
	v_mov_b32_e32 v145, v213
	v_mov_b32_e32 v146, v133
	v_mfma_f32_16x16x32_f16 v[72:75], v[240:243], v[134:137], v[190:193]
	v_mfma_f32_16x16x32_f16 v[104:107], v[244:247], v[134:137], v[194:197]
	v_or_b32_e32 v134, v148, v128
	v_lshlrev_b32_e32 v135, 4, v153
	v_mov_b32_e32 v148, 0x80
	v_mfma_f32_16x16x32_f16 v[20:23], v[228:231], v[210:213], v[112:115]
	v_mfma_f32_16x16x32_f16 v[112:115], v[236:239], v[56:59], v[138:141]
	s_nop 2
	v_sub_u32_e32 v138, v134, v135
	v_subrev_u32_e32 v138, s1, v138
	v_mfma_f32_16x16x32_f16 v[48:51], v[228:231], v[248:251], v[60:63]
	v_add_u32_e32 v161, 0, v138
	s_movk_i32 s1, 0xf080
	v_mfma_f32_16x16x32_f16 v[44:47], v[236:239], v[248:251], v[64:67]
	v_mfma_f32_16x16x32_f16 v[12:15], v[240:243], v[210:213], v[120:123]
	v_mfma_f32_16x16x32_f16 v[120:123], v[244:247], v[56:59], v[162:165]
	v_mfma_f32_16x16x32_f16 v[68:71], v[228:231], v[130:133], v[166:169]
	s_nop 1
	v_lshl_or_b32 v162, v151, 3, v148
	v_mfma_f32_16x16x32_f16 v[64:67], v[236:239], v[130:133], v[170:173]
	v_mfma_f32_16x16x32_f16 v[60:63], v[240:243], v[130:133], v[174:177]
	v_mfma_f32_16x16x32_f16 v[56:59], v[244:247], v[130:133], v[178:181]
	v_mfma_f32_16x16x32_f16 v[130:133], v[228:231], v[144:147], v[198:201]
	v_mfma_f32_16x16x32_f16 v[134:137], v[236:239], v[144:147], v[202:205]
	v_mfma_f32_16x16x32_f16 v[138:141], v[240:243], v[144:147], v[224:227]
	v_mfma_f32_16x16x32_f16 v[146:149], v[244:247], v[144:147], v[232:235]
	.p2align	6

;   DI bool next(int i, Unit2& u) const { const int it = xs.item(i); if (it < 0) return false; u.pm = (it & 31) >> 2; u.pn = (it >> 5) * 4 + (it & 3); return true; }
; template <bool HEADPERM, class Sched, class Epi>
; DI void gemm256_stream(char* lds, const h16* __restrict__ Ab, int lda, const h16* __restrict__ Bb, int ldb, int K, const Sched& S, const Epi& E) {
;     ...
;     const bool has_next = S.next(ui + 1, nxt);
;     const char* nA = has_next ? (const char*)Ab + (size_t)nxt.pm * tstepA : cA;
;     const char* nB = has_next ? (const char*)Bb + (size_t)nxt.pn * tstepB : cB;
;     ...
; #pragma unroll
;     for (int a = 0; a < 2; ++a)
; #pragma unroll
;       for (int b = 0; b < 2; ++b)
; #pragma unroll
;         for (int m = 0; m < 4; ++m)
; #pragma unroll
;           for (int n = 0; n < 2; ++n) acc[a][b][m][n] = f32x4{0.f, 0.f, 0.f, 0.f};
;     cur = nxt; cA = nA; cB = nB; ++ui;
.LBB0_500:
	s_bfe_u32 s87, s24, 0x30002
	s_mul_i32 s24, s87, 0x88000
	s_add_u32 s44, s53, s24
	s_addc_u32 s45, s80, 0
	s_and_b64 s[24:25], s[40:41], exec
	s_cselect_b32 vcc_lo, s45, s39
	s_cselect_b32 vcc_hi, s44, s38
	s_add_u32 s76, s2, 0x100
	v_mov_b32_e32 v0, 0
	s_addc_u32 s81, s3, 0
	s_mov_b32 s77, -2
	v_mov_b32_e32 v1, v0
	v_mov_b32_e32 v2, v0
	v_mov_b32_e32 v3, v0
	v_mov_b32_e32 v4, v0
	v_mov_b32_e32 v5, v0
	v_mov_b32_e32 v6, v0
	v_mov_b32_e32 v7, v0
	v_mov_b32_e32 v16, v0
	v_mov_b32_e32 v17, v0
	v_mov_b32_e32 v18, v0
	v_mov_b32_e32 v19, v0
	v_mov_b32_e32 v20, v0
	v_mov_b32_e32 v21, v0
	v_mov_b32_e32 v22, v0
	v_mov_b32_e32 v23, v0
	v_mov_b32_e32 v32, v0
	v_mov_b32_e32 v33, v0
	v_mov_b32_e32 v34, v0
	v_mov_b32_e32 v35, v0
	v_mov_b32_e32 v36, v0
	v_mov_b32_e32 v37, v0
	v_mov_b32_e32 v38, v0
	v_mov_b32_e32 v39, v0
	v_mov_b32_e32 v48, v0
	v_mov_b32_e32 v49, v0
	v_mov_b32_e32 v50, v0
	v_mov_b32_e32 v51, v0
	v_mov_b32_e32 v52, v0
	v_mov_b32_e32 v53, v0
	v_mov_b32_e32 v54, v0
	v_mov_b32_e32 v55, v0
	v_mov_b32_e32 v8, v0
	v_mov_b32_e32 v9, v0
	v_mov_b32_e32 v10, v0
	v_mov_b32_e32 v11, v0
	v_mov_b32_e32 v12, v0
	v_mov_b32_e32 v13, v0
	v_mov_b32_e32 v14, v0
	v_mov_b32_e32 v15, v0
	v_mov_b32_e32 v24, v0
	v_mov_b32_e32 v25, v0
	v_mov_b32_e32 v26, v0
	v_mov_b32_e32 v27, v0
	v_mov_b32_e32 v28, v0
	v_mov_b32_e32 v29, v0
	v_mov_b32_e32 v30, v0
	v_mov_b32_e32 v31, v0
	v_mov_b32_e32 v40, v0
	v_mov_b32_e32 v41, v0
	v_mov_b32_e32 v42, v0
	v_mov_b32_e32 v43, v0
	v_mov_b32_e32 v44, v0
	v_mov_b32_e32 v45, v0
	v_mov_b32_e32 v46, v0
	v_mov_b32_e32 v47, v0
	v_mov_b32_e32 v56, v0
	v_mov_b32_e32 v57, v0
	v_mov_b32_e32 v58, v0
	v_mov_b32_e32 v59, v0
	v_mov_b32_e32 v60, v0
	v_mov_b32_e32 v61, v0
	v_mov_b32_e32 v62, v0
	v_mov_b32_e32 v63, v0
	v_mov_b32_e32 v64, v0
	v_mov_b32_e32 v65, v0
	v_mov_b32_e32 v66, v0
	v_mov_b32_e32 v67, v0
	v_mov_b32_e32 v68, v0
	v_mov_b32_e32 v69, v0
	v_mov_b32_e32 v70, v0
	v_mov_b32_e32 v71, v0
	v_mov_b32_e32 v80, v0
	v_mov_b32_e32 v81, v0
	v_mov_b32_e32 v82, v0
	v_mov_b32_e32 v83, v0
	v_mov_b32_e32 v84, v0
	v_mov_b32_e32 v85, v0
	v_mov_b32_e32 v86, v0
	v_mov_b32_e32 v87, v0
	v_mov_b32_e32 v96, v0
	v_mov_b32_e32 v97, v0
	v_mov_b32_e32 v98, v0
	v_mov_b32_e32 v99, v0
	v_mov_b32_e32 v100, v0
	v_mov_b32_e32 v101, v0
	v_mov_b32_e32 v102, v0
	v_mov_b32_e32 v103, v0
	v_mov_b32_e32 v112, v0
	v_mov_b32_e32 v113, v0
	v_mov_b32_e32 v114, v0
	v_mov_b32_e32 v115, v0
	v_mov_b32_e32 v116, v0
	v_mov_b32_e32 v117, v0
	v_mov_b32_e32 v118, v0
	v_mov_b32_e32 v119, v0
	v_mov_b32_e32 v72, v0
	v_mov_b32_e32 v73, v0
	v_mov_b32_e32 v74, v0
	v_mov_b32_e32 v75, v0
	v_mov_b32_e32 v76, v0
	v_mov_b32_e32 v77, v0
	v_mov_b32_e32 v78, v0
	v_mov_b32_e32 v79, v0
	v_mov_b32_e32 v88, v0
	v_mov_b32_e32 v89, v0
	v_mov_b32_e32 v90, v0
	v_mov_b32_e32 v91, v0
	v_mov_b32_e32 v92, v0
	v_mov_b32_e32 v93, v0
	v_mov_b32_e32 v94, v0
	v_mov_b32_e32 v95, v0
	v_mov_b32_e32 v104, v0
	v_mov_b32_e32 v105, v0
	v_mov_b32_e32 v106, v0
	v_mov_b32_e32 v107, v0
	v_mov_b32_e32 v108, v0
	v_mov_b32_e32 v109, v0
	v_mov_b32_e32 v110, v0
	v_mov_b32_e32 v111, v0
	v_mov_b32_e32 v120, v0
	v_mov_b32_e32 v121, v0
	v_mov_b32_e32 v122, v0
	v_mov_b32_e32 v123, v0
	v_mov_b32_e32 v124, v0
	v_mov_b32_e32 v125, v0
	v_mov_b32_e32 v126, v0
	v_mov_b32_e32 v127, v0
	.p2align	6

; DI size_t wbase(int layer) { return (layer & 1) ? WS_W1 : WS_WINT; }
; DI void wait_vm0() { asm volatile("s_waitcnt vmcnt(0)" ::: "memory"); }
; DI int otid() { int t = threadIdx.x; asm volatile("" : "+v"(t)); return t; }
; template <int MB, bool SWAP>
; DI void gemm_kloop(f32x16 (&acc)[MB][2], const h16* __restrict__ A, int lda, const h16* __restrict__ B, int ldb, int K, char* lds) {
;     ...
;   const int tid = otid(), w = tid >> 6, lane = tid & 63;
;   const int wr = w >> 2, wc = w & 3;
;   const int lrow = w * 8 + (lane >> 3), pch = lane & 7;
;   const int gch = pch ^ ((lrow >> 1) & 7);
;   const unsigned voa = (unsigned)(lrow * lda + gch * 8) * 2u, vob = (unsigned)(lrow * ldb + gch * 8) * 2u;
;   const int lofs = lrow * 128 + pch * 16;
;   const int r32 = lane & 31, hh = lane >> 5, sw = (r32 >> 1) & 7;
;   const int a_rd = (wr * 32 * MB + r32) * 128;
;   const int b_rd = A_BYTES + (wc * 64 + r32) * 128;
;   const int nk = K >> 6;
;   constexpr int NP = MB + 4;
;   auto piece = [&](int p, int kt, int buf) {
;     char* s = lds + buf * STAGE;
;     if (p < MB) __builtin_amdgcn_global_load_lds((const unsigned*)((const char*)(A + (size_t)p * 64 * lda + kt * 64) + voa), (unsigned*)(s + p * 8192 + lofs), 16, 0, 0);
;     else __builtin_amdgcn_global_load_lds((const unsigned*)((const char*)(B + (size_t)(p - MB) * 64 * ldb + kt * 64) + vob), (unsigned*)(s + A_BYTES + (p - MB) * 8192 + lofs), 16, 0, 0);
;   };
;   wait_vm0();
; #pragma unroll
;   for (int p = 0; p < NP; ++p) piece(p, 0, 0);
; #pragma unroll
;   for (int p = 0; p < NP; ++p) piece(p, 1, 1);
; template <int MB>
; DI void out_tile(const Params& P, int layer, int row0, int nt, char* smem) {
;   const h16* mg = (const h16*)(P.ws + WS_R1);
;   const h16* woutT = (const h16*)(P.ws + wbase(layer) + OFF_WOUTT);
;   const float* mods = (const float*)(P.ws + WS_MODS) + (size_t)layer * 17 * 3072;
;   float* ctxw = (float*)(P.ws + WS_CTXW);
;   f32x16 acc[MB][2];
;   zero_acc<MB>(acc);
;   gemm_kloop<MB, true>(acc, mg + (size_t)row0 * LDH, LDH, woutT + (size_t)(nt * 256) * LDH, LDH, D, smem);
.LBB0_721:
	s_add_i32 s2, s39, s81
	s_cmp_ge_i32 s2, s70
	s_cbranch_scc1 .LBB0_720
	v_mov_b32_e32 v6, v208
	s_bfe_u32 s24, s38, 0x20003
	v_ashrrev_i32_e32 v7, 3, v6
	v_bfe_u32 v8, v6, 3, 3
	v_and_or_b32 v0, v7, -8, v8
	v_lshrrev_b32_e32 v1, 1, v0
	v_xor_b32_e32 v1, v1, v6
	v_lshlrev_b32_e32 v1, 3, v1
	v_mul_lo_u32 v2, v0, s6
	v_and_b32_e32 v9, 56, v1
	v_or_b32_e32 v1, v9, v2
	s_ashr_i32 s52, s2, 2
	v_lshlrev_b32_e32 v128, 1, v1
	v_lshlrev_b32_e32 v1, 4, v6
	s_mul_i32 s33, s24, 0x88000
	s_and_b32 s24, s52, 0x1fffff8
	s_and_b32 s25, s2, 7
	v_and_b32_e32 v1, 0x70, v1
	s_and_b32 s3, s97, 7
	s_or_b32 s24, s24, s25
	v_lshl_or_b32 v10, v0, 7, v1
	s_lshl_b32 s3, s3, 7
	s_bfe_u32 s75, s2, 0x20003
	s_lshl_b32 s2, s24, 7
	s_mul_i32 s24, s24, 0x44000
	v_add_u32_e32 v74, 0, v10
	s_mul_hi_i32 s25, s2, 0x880
	s_add_u32 s24, s48, s24
	v_readfirstlane_b32 s53, v74
	s_addc_u32 s25, s49, s25
	s_nop 0
	s_mov_b32 m0, s53
	v_add_u32_e32 v13, 0x2000, v74
	v_lshl_add_u64 v[2:3], s[24:25], 0, v[128:129]
	global_load_lds_dwordx4 v128, s[24:25]
	s_mov_b64 s[54:55], 0x22000
	v_readfirstlane_b32 s24, v13
	s_mul_i32 s50, s75, 0x88000
	v_lshl_add_u64 v[4:5], v[2:3], 0, s[54:55]
	s_mov_b32 m0, s24
	s_add_u32 s50, s87, s50
	v_and_b32_e32 v0, 31, v6
	v_lshrrev_b32_e32 v1, 2, v6
	global_load_lds_dwordx4 v[4:5], off
	v_add_u32_e32 v4, 0x4000, v74
	s_addc_u32 s51, s96, 0
	v_and_or_b32 v12, v1, s7, v0
	v_lshlrev_b32_e32 v0, 7, v6
	v_readfirstlane_b32 s24, v4
	v_add_u32_e32 v13, 0x6000, v74
	v_and_b32_e32 v68, 0x6f80, v0
	v_lshl_add_u64 v[0:1], s[50:51], 0, v[128:129]
	s_mov_b32 m0, s24
	v_readfirstlane_b32 s24, v13
	global_load_lds_dwordx4 v128, s[50:51]
	v_lshl_add_u64 v[4:5], v[0:1], 0, s[54:55]
	s_mov_b32 m0, s24
	s_mov_b64 s[24:25], 0x44000
	v_add_u32_e32 v13, 0x8000, v74
	global_load_lds_dwordx4 v[4:5], off
	v_lshl_add_u64 v[4:5], v[0:1], 0, s[24:25]
	v_readfirstlane_b32 s24, v13
	s_mov_b32 m0, s24
	s_mov_b64 s[24:25], 0x66000
	v_add_u32_e32 v13, 0xa000, v74
	global_load_lds_dwordx4 v[4:5], off
	v_lshl_add_u64 v[4:5], v[0:1], 0, s[24:25]
	v_readfirstlane_b32 s24, v13
	v_lshlrev_b32_e32 v70, 7, v12
	v_add_u32_e32 v12, 0xc000, v74
	s_mov_b32 m0, s24
	v_readfirstlane_b32 s24, v12
	global_load_lds_dwordx4 v[4:5], off
	v_lshl_add_u64 v[4:5], v[2:3], 0, s[22:23]
	s_mov_b32 m0, s24
	s_mov_b64 s[50:51], 0x22080
	global_load_lds_dwordx4 v[4:5], off
	v_add_u32_e32 v4, 0xe000, v74
	v_lshl_add_u64 v[2:3], v[2:3], 0, s[50:51]
	v_readfirstlane_b32 s24, v4
	v_add_u32_e32 v4, s8, v10
	s_mov_b32 m0, s24
	v_readfirstlane_b32 s24, v4
	v_add_u32_e32 v4, s9, v10
	global_load_lds_dwordx4 v[2:3], off
	v_lshl_add_u64 v[2:3], v[0:1], 0, s[22:23]
	s_mov_b32 m0, s24
	v_readfirstlane_b32 s24, v4
	global_load_lds_dwordx4 v[2:3], off
	v_lshl_add_u64 v[2:3], v[0:1], 0, s[50:51]
	s_mov_b32 m0, s24
	s_mov_b64 s[24:25], 0x44080
	v_add_u32_e32 v4, s79, v10
	global_load_lds_dwordx4 v[2:3], off
	v_lshl_add_u64 v[2:3], v[0:1], 0, s[24:25]
	v_readfirstlane_b32 s24, v4
	s_mov_b32 m0, s24
	s_mov_b64 s[24:25], 0x66080
	global_load_lds_dwordx4 v[2:3], off
	v_add_u32_e32 v2, s10, v10
	v_lshl_add_u64 v[0:1], v[0:1], 0, s[24:25]
	v_readfirstlane_b32 s24, v2
	s_mov_b32 m0, s24
	v_lshrrev_b32_e32 v11, 1, v6
	global_load_lds_dwordx4 v[0:1], off
	v_bfe_u32 v13, v6, 5, 1
	v_bfe_u32 v0, v6, 1, 3
	v_bitop3_b32 v1, v13, v11, 7 bitop3:0x78
	v_lshlrev_b32_e32 v73, 4, v1
	v_bitop3_b32 v1, v13, v0, 2 bitop3:0x36
	v_lshlrev_b32_e32 v72, 4, v1
	v_bitop3_b32 v1, v13, v0, 4 bitop3:0x36
	v_bitop3_b32 v0, v13, v0, 6 bitop3:0x36
	s_lshl_b32 s24, s52, 7
	v_lshlrev_b32_e32 v69, 4, v0
	s_and_b32 s24, s24, 0xfffffc00
	v_lshrrev_b32_e32 v0, 3, v7
	s_or_b32 s3, s24, s3
	v_mul_lo_u32 v0, v0, s11
	v_readlane_b32 s52, v253, 1
	s_mul_hi_i32 s25, s3, 0x880
	s_mulk_i32 s3, 0x880
	v_mad_u32_u24 v0, v8, s6, v0
	v_readlane_b32 s66, v253, 15
	v_or_b32_e32 v0, v0, v9
	v_readlane_b32 s67, v253, 16
	s_add_u32 s24, s66, s3
	v_lshlrev_b32_e32 v128, 1, v0
	s_addc_u32 s25, s67, s25
	v_lshl_add_u64 v[64:65], s[24:25], 0, v[128:129]
	s_add_u32 s24, s84, s33
	v_readlane_b32 s53, v253, 2
	v_readlane_b32 s54, v253, 3
	v_readlane_b32 s55, v253, 4
	v_readlane_b32 s56, v253, 5
	v_readlane_b32 s57, v253, 6
	v_readlane_b32 s58, v253, 7
	v_readlane_b32 s59, v253, 8
	v_readlane_b32 s60, v253, 9
	v_readlane_b32 s61, v253, 10
	v_readlane_b32 s62, v253, 11
	v_readlane_b32 s63, v253, 12
	s_addc_u32 s25, s86, 0
	v_mov_b32_e32 v0, 0
	v_lshlrev_b32_e32 v71, 4, v1
	v_lshl_add_u64 v[66:67], s[24:25], 0, v[128:129]
	s_mov_b32 s3, 0
	s_mov_b64 s[50:51], 0
	v_mov_b32_e32 v1, v0
	v_mov_b32_e32 v2, v0
	v_mov_b32_e32 v3, v0
	v_mov_b32_e32 v4, v0
	v_mov_b32_e32 v5, v0
	v_mov_b32_e32 v6, v0
	v_mov_b32_e32 v7, v0
	v_mov_b32_e32 v8, v0
	v_mov_b32_e32 v9, v0
	v_mov_b32_e32 v10, v0
	v_mov_b32_e32 v11, v0
	v_mov_b32_e32 v12, v0
	v_mov_b32_e32 v13, v0
	v_mov_b32_e32 v14, v0
	v_mov_b32_e32 v15, v0
	v_mov_b32_e32 v16, v0
	v_mov_b32_e32 v17, v0
	v_mov_b32_e32 v18, v0
	v_mov_b32_e32 v19, v0
	v_mov_b32_e32 v20, v0
	v_mov_b32_e32 v21, v0
	v_mov_b32_e32 v22, v0
	v_mov_b32_e32 v23, v0
	v_mov_b32_e32 v24, v0
	v_mov_b32_e32 v25, v0
	v_mov_b32_e32 v26, v0
	v_mov_b32_e32 v27, v0
	v_mov_b32_e32 v28, v0
	v_mov_b32_e32 v29, v0
	v_mov_b32_e32 v30, v0
	v_mov_b32_e32 v31, v0
	v_mov_b32_e32 v32, v0
	v_mov_b32_e32 v33, v0
	v_mov_b32_e32 v34, v0
	v_mov_b32_e32 v35, v0
	v_mov_b32_e32 v36, v0
	v_mov_b32_e32 v37, v0
	v_mov_b32_e32 v38, v0
	v_mov_b32_e32 v39, v0
	v_mov_b32_e32 v40, v0
	v_mov_b32_e32 v41, v0
	v_mov_b32_e32 v42, v0
	v_mov_b32_e32 v43, v0
	v_mov_b32_e32 v44, v0
	v_mov_b32_e32 v45, v0
	v_mov_b32_e32 v46, v0
	v_mov_b32_e32 v47, v0
	v_mov_b32_e32 v48, v0
	v_mov_b32_e32 v49, v0
	v_mov_b32_e32 v50, v0
	v_mov_b32_e32 v51, v0
	v_mov_b32_e32 v52, v0
	v_mov_b32_e32 v53, v0
	v_mov_b32_e32 v54, v0
	v_mov_b32_e32 v55, v0
	v_mov_b32_e32 v56, v0
	v_mov_b32_e32 v57, v0
	v_mov_b32_e32 v58, v0
	v_mov_b32_e32 v59, v0
	v_mov_b32_e32 v60, v0
	v_mov_b32_e32 v61, v0
	v_mov_b32_e32 v62, v0
	v_mov_b32_e32 v63, v0
	s_mov_b64 s[52:53], 0x14e8100
	s_mov_b64 s[54:55], 0x7f88100
	s_mov_b64 s[56:57], 0x7f66100
	s_mov_b64 s[58:59], 0x150a100
	s_mov_b64 s[60:61], 0x154e100
	s_mov_b64 s[62:63], 0x152c100
	v_readlane_b32 s64, v253, 13
	v_readlane_b32 s65, v253, 14
	v_readfirstlane_b32 s25, v208
	s_nop 0
	s_lshr_b32 s25, s25, 8
	s_cmp_lg_u32 s25, 0
	s_cbranch_scc1 .Lstg723_top
	.p2align	6
; template <int MB, bool SWAP>
; DI void gemm_kloop(f32x16 (&acc)[MB][2], const h16* __restrict__ A, int lda, const h16* __restrict__ B, int ldb, int K, char* lds) {
;     ...
;   auto piece = [&](int p, int kt, int buf) {
;     char* s = lds + buf * STAGE;
;     if (p < MB) __builtin_amdgcn_global_load_lds((const unsigned*)((const char*)(A + (size_t)p * 64 * lda + kt * 64) + voa), (unsigned*)(s + p * 8192 + lofs), 16, 0, 0);
;     else __builtin_amdgcn_global_load_lds((const unsigned*)((const char*)(B + (size_t)(p - MB) * 64 * ldb + kt * 64) + vob), (unsigned*)(s + A_BYTES + (p - MB) * 8192 + lofs), 16, 0, 0);
;   };
;     ...
;   for (int kt = 0; kt < nk; ++kt) {
;     if (kt + 1 < nk) { if (MB == 2) asm volatile("s_waitcnt vmcnt(6)" ::: "memory"); else asm volatile("s_waitcnt vmcnt(5)" ::: "memory"); }
;     else wait_vm0();
;     __syncthreads();
;     const char* s = lds + cur * STAGE;
;     const int nbuf = cur == 0 ? 2 : cur - 1;
;     const bool more = kt + 2 < nk;
;     half8 af[2][MB], bf[2][2];
; #pragma unroll
;     for (int mb = 0; mb < MB; ++mb) af[0][mb] = *(const half8*)(s + a_rd + mb * 4096 + (((0 + hh) ^ sw) * 16));
; #pragma unroll
;     for (int nb = 0; nb < 2; ++nb) bf[0][nb] = *(const half8*)(s + b_rd + nb * 4096 + (((0 + hh) ^ sw) * 16));
; #pragma unroll
;     for (int ks = 0; ks < 4; ++ks) {
;       if (ks < 3) {
; #pragma unroll
;         for (int mb = 0; mb < MB; ++mb) af[(ks + 1) & 1][mb] = *(const half8*)(s + a_rd + mb * 4096 + (((2 * (ks + 1) + hh) ^ sw) * 16));
; #pragma unroll
;         for (int nb = 0; nb < 2; ++nb) bf[(ks + 1) & 1][nb] = *(const half8*)(s + b_rd + nb * 4096 + (((2 * (ks + 1) + hh) ^ sw) * 16));
;       }
;       if (more) {
;         if (2 * ks < NP) piece(2 * ks, kt + 2, nbuf);
;         if (2 * ks + 1 < NP) piece(2 * ks + 1, kt + 2, nbuf);
;       }
;       __builtin_amdgcn_sched_barrier(0);
;       __builtin_amdgcn_s_setprio(1);
; #pragma unroll
;       for (int mb = 0; mb < MB; ++mb)
; #pragma unroll
;         for (int nb = 0; nb < 2; ++nb)
;           acc[mb][nb] = SWAP ? __builtin_amdgcn_mfma_f32_32x32x16_f16(bf[ks & 1][nb], af[ks & 1][mb], acc[mb][nb], 0, 0, 0)
;                              : __builtin_amdgcn_mfma_f32_32x32x16_f16(af[ks & 1][mb], bf[ks & 1][nb], acc[mb][nb], 0, 0, 0);
;       __builtin_amdgcn_s_setprio(0);
;       __builtin_amdgcn_sched_barrier(0);
;     }
;     cur = cur == 2 ? 0 : cur + 1;
;   }
.LBB0_723:
	s_mul_i32 s24, s3, 0xc000
	s_add_i32 s25, s24, 0
	s_add_i32 s24, s24, 0xffff4000
	s_cmp_lg_u32 s3, 0
	s_cselect_b32 s24, s24, 0x18000
	v_add_u32_e32 v115, s24, v74
	v_add_u32_e32 v75, s25, v70
	v_add_u32_e32 v114, s25, v68
	v_add_u32_e32 v112, 0x2000, v115
	v_lshl_add_u64 v[108:109], v[64:65], 0, s[50:51]
	v_readfirstlane_b32 s24, v115
	v_add_u32_e32 v80, v75, v73
	v_add_u32_e32 v88, v114, v73
	v_add_u32_e32 v96, v75, v72
	v_add_u32_e32 v104, v114, v72
	v_lshl_add_u64 v[110:111], v[108:109], 0, s[54:55]
	v_lshl_add_u64 v[108:109], v[108:109], 0, s[56:57]
	s_mov_b32 m0, s24
	v_readfirstlane_b32 s24, v112
	s_waitcnt vmcnt(6)
	s_waitcnt lgkmcnt(0)
	s_barrier
	ds_read_b128 v[76:79], v80
	ds_read_b128 v[80:83], v80 offset:4096
	ds_read_b128 v[84:87], v88 offset:16384
	ds_read_b128 v[88:91], v88 offset:20480
	ds_read_b128 v[92:95], v96
	ds_read_b128 v[96:99], v96 offset:4096
	ds_read_b128 v[100:103], v104 offset:16384
	ds_read_b128 v[104:107], v104 offset:20480
	global_load_lds_dwordx4 v[108:109], off
	s_mov_b32 m0, s24
	v_lshl_add_u64 v[108:109], v[66:67], 0, s[50:51]
	global_load_lds_dwordx4 v[110:111], off
	v_lshl_add_u64 v[110:111], v[108:109], 0, s[52:53]
	s_setprio 1
	s_waitcnt lgkmcnt(0)
	v_mfma_f32_32x32x16_f16 v[48:63], v[84:87], v[76:79], v[48:63]
	v_mfma_f32_32x32x16_f16 v[32:47], v[88:91], v[76:79], v[32:47]
	v_mfma_f32_32x32x16_f16 v[16:31], v[84:87], v[80:83], v[16:31]
	v_mfma_f32_32x32x16_f16 v[0:15], v[88:91], v[80:83], v[0:15]
	s_setprio 0
	v_add_u32_e32 v117, 0x4000, v115
	v_add_u32_e32 v116, 0x6000, v115
	v_readfirstlane_b32 s24, v117
	v_add_u32_e32 v80, v75, v71
	v_add_u32_e32 v88, v114, v71
	s_mov_b32 m0, s24
	v_readfirstlane_b32 s24, v116
	ds_read_b128 v[76:79], v80
	ds_read_b128 v[80:83], v80 offset:4096
	ds_read_b128 v[84:87], v88 offset:16384
	ds_read_b128 v[88:91], v88 offset:20480
	v_lshl_add_u64 v[112:113], v[108:109], 0, s[58:59]
	global_load_lds_dwordx4 v[110:111], off
	s_mov_b32 m0, s24
	s_nop 0
	global_load_lds_dwordx4 v[112:113], off
	s_setprio 1
	v_mfma_f32_32x32x16_f16 v[48:63], v[100:103], v[92:95], v[48:63]
	v_mfma_f32_32x32x16_f16 v[32:47], v[104:107], v[92:95], v[32:47]
	v_mfma_f32_32x32x16_f16 v[16:31], v[100:103], v[96:99], v[16:31]
	v_mfma_f32_32x32x16_f16 v[0:15], v[104:107], v[96:99], v[0:15]
	s_setprio 0
	v_add_u32_e32 v75, v75, v69
	ds_read_b128 v[92:95], v75
	ds_read_b128 v[96:99], v75 offset:4096
	v_add_u32_e32 v75, v114, v69
	v_add_u32_e32 v112, 0x8000, v115
	ds_read_b128 v[100:103], v75 offset:16384
	ds_read_b128 v[104:107], v75 offset:20480
	v_add_u32_e32 v75, 0xa000, v115
	v_readfirstlane_b32 s24, v112
	v_lshl_add_u64 v[110:111], v[108:109], 0, s[60:61]
	v_lshl_add_u64 v[108:109], v[108:109], 0, s[62:63]
	s_mov_b32 m0, s24
	v_readfirstlane_b32 s24, v75
	global_load_lds_dwordx4 v[108:109], off
	s_mov_b32 m0, s24
	s_nop 0
	global_load_lds_dwordx4 v[110:111], off
	s_setprio 1
	s_waitcnt lgkmcnt(0)
	v_mfma_f32_32x32x16_f16 v[48:63], v[84:87], v[76:79], v[48:63]
	v_mfma_f32_32x32x16_f16 v[32:47], v[88:91], v[76:79], v[32:47]
	v_mfma_f32_32x32x16_f16 v[16:31], v[84:87], v[80:83], v[16:31]
	v_mfma_f32_32x32x16_f16 v[0:15], v[88:91], v[80:83], v[0:15]
	s_setprio 0
	s_setprio 1
	v_mfma_f32_32x32x16_f16 v[48:63], v[100:103], v[92:95], v[48:63]
	v_mfma_f32_32x32x16_f16 v[32:47], v[104:107], v[92:95], v[32:47]
	v_mfma_f32_32x32x16_f16 v[16:31], v[100:103], v[96:99], v[16:31]
	v_mfma_f32_32x32x16_f16 v[0:15], v[104:107], v[96:99], v[0:15]
	s_setprio 0
	s_add_i32 s24, s3, 1
	s_cmp_lg_u32 s3, 2
	s_cselect_b32 s3, s24, 0
	s_add_u32 s50, s50, 0x80
	s_addc_u32 s51, s51, 0
	s_cmpk_eq_i32 s50, 0x700
	s_cbranch_scc0 .LBB0_723
	s_branch .Lstg723_join
	.p2align	6
